# scan: per-step LDS wait moved to the end of the step (just before the next step's first use)
# baseline (speedup 1.0000x reference)
.LBB0_685:
	ds_read_b128 v[164:167], v5 offset:0
	ds_read_b128 v[168:171], v5 offset:256
	ds_read_b128 v[172:175], v5 offset:512
	ds_read_b128 v[176:179], v5 offset:768
	ds_read_b128 v[180:183], v5 offset:1024
	ds_read_b32 v184, v9 offset:0
	ds_read_b128 v[186:189], v5 offset:1536
	ds_read_b128 v[190:193], v5 offset:1792
	ds_read_b128 v[194:197], v5 offset:2048
	ds_read_b128 v[198:201], v5 offset:2304
	ds_read_b128 v[202:205], v5 offset:2560
	ds_read_b32 v206, v9 offset:1536
	s_waitcnt lgkmcnt(6)
	v_pk_mul_f32 v[144:145], v[138:139], v[164:165]
	v_pk_fma_f32 v[144:145], v[140:141], v[166:167], v[144:145]
	v_add_f32 v146, v144, v145
	ds_read_b128 v[208:211], v5 offset:3072
	ds_read_b128 v[212:215], v5 offset:3328
	ds_read_b128 v[216:219], v5 offset:3584
	ds_read_b128 v[220:223], v5 offset:3840
	ds_read_b128 v[224:227], v5 offset:4096
	ds_read_b32 v228, v9 offset:3072
	v_add_f32_dpp v146, v146, v146 quad_perm:[1,0,3,2] row_mask:0xf bank_mask:0xf bound_ctrl:1
	s_nop 0
	s_nop 0
	v_add_f32_dpp v146, v146, v146 quad_perm:[2,3,0,1] row_mask:0xf bank_mask:0xf bound_ctrl:1
	s_nop 0
	v_pk_mul_f32 v[176:177], v[176:177], v[184:185] op_sel_hi:[1,0]
	v_add_f32_dpp v146, v146, v146 row_half_mirror row_mask:0xf bank_mask:0xf bound_ctrl:1
	v_pk_mul_f32 v[178:179], v[178:179], v[184:185] op_sel_hi:[1,0]
	s_nop 0
	v_add_f32_dpp v146, v146, v146 row_mirror row_mask:0xf bank_mask:0xf bound_ctrl:1
	v_pk_fma_f32 v[176:177], v[146:147], v[168:169], v[176:177] op_sel_hi:[0,1,1] neg_lo:[1,0,0] neg_hi:[1,0,0]
	v_pk_fma_f32 v[178:179], v[146:147], v[170:171], v[178:179] op_sel_hi:[0,1,1] neg_lo:[1,0,0] neg_hi:[1,0,0]
	v_pk_fma_f32 v[138:139], v[138:139], v[172:173], v[176:177]
	v_pk_fma_f32 v[140:141], v[140:141], v[174:175], v[178:179]
	s_waitcnt lgkmcnt(6)
	v_pk_mul_f32 v[144:145], v[138:139], v[186:187]
	v_pk_fma_f32 v[144:145], v[140:141], v[188:189], v[144:145]
	v_add_f32 v146, v144, v145
	ds_read_b128 v[230:233], v5 offset:4608
	ds_read_b128 v[234:237], v5 offset:4864
	ds_read_b128 v[238:241], v5 offset:5120
	ds_read_b128 v[242:245], v5 offset:5376
	ds_read_b128 v[246:249], v5 offset:5632
	ds_read_b32 v250, v9 offset:4608
	v_add_f32_dpp v146, v146, v146 quad_perm:[1,0,3,2] row_mask:0xf bank_mask:0xf bound_ctrl:1
	v_pk_mul_f32 v[180:181], v[138:139], v[180:181]
	v_pk_fma_f32 v[180:181], v[140:141], v[182:183], v[180:181]
	v_add_f32_dpp v146, v146, v146 quad_perm:[2,3,0,1] row_mask:0xf bank_mask:0xf bound_ctrl:1
	v_add_f32 v148, v180, v181
	v_pk_mul_f32 v[198:199], v[198:199], v[206:207] op_sel_hi:[1,0]
	v_add_f32_dpp v146, v146, v146 row_half_mirror row_mask:0xf bank_mask:0xf bound_ctrl:1
	v_pk_mul_f32 v[200:201], v[200:201], v[206:207] op_sel_hi:[1,0]
	s_nop 0
	v_add_f32_dpp v146, v146, v146 row_mirror row_mask:0xf bank_mask:0xf bound_ctrl:1
	v_pk_fma_f32 v[198:199], v[146:147], v[190:191], v[198:199] op_sel_hi:[0,1,1] neg_lo:[1,0,0] neg_hi:[1,0,0]
	v_pk_fma_f32 v[200:201], v[146:147], v[192:193], v[200:201] op_sel_hi:[0,1,1] neg_lo:[1,0,0] neg_hi:[1,0,0]
	v_pk_fma_f32 v[138:139], v[138:139], v[194:195], v[198:199]
	v_pk_fma_f32 v[140:141], v[140:141], v[196:197], v[200:201]
	s_waitcnt lgkmcnt(6)
	v_pk_mul_f32 v[144:145], v[138:139], v[208:209]
	v_pk_fma_f32 v[144:145], v[140:141], v[210:211], v[144:145]
	v_add_f32 v146, v144, v145
	ds_read_b128 v[164:167], v5 offset:6144
	ds_read_b128 v[168:171], v5 offset:6400
	ds_read_b128 v[172:175], v5 offset:6656
	ds_read_b128 v[176:179], v5 offset:6912
	ds_read_b128 v[180:183], v5 offset:7168
	ds_read_b32 v184, v9 offset:6144
	v_add_f32_dpp v146, v146, v146 quad_perm:[1,0,3,2] row_mask:0xf bank_mask:0xf bound_ctrl:1
	v_pk_mul_f32 v[202:203], v[138:139], v[202:203]
	v_pk_fma_f32 v[202:203], v[140:141], v[204:205], v[202:203]
	v_add_f32_dpp v146, v146, v146 quad_perm:[2,3,0,1] row_mask:0xf bank_mask:0xf bound_ctrl:1
	v_add_f32 v149, v202, v203
	v_pk_mul_f32 v[220:221], v[220:221], v[228:229] op_sel_hi:[1,0]
	v_add_f32_dpp v146, v146, v146 row_half_mirror row_mask:0xf bank_mask:0xf bound_ctrl:1
	v_pk_mul_f32 v[222:223], v[222:223], v[228:229] op_sel_hi:[1,0]
	s_nop 0
	v_add_f32_dpp v146, v146, v146 row_mirror row_mask:0xf bank_mask:0xf bound_ctrl:1
	v_pk_fma_f32 v[220:221], v[146:147], v[212:213], v[220:221] op_sel_hi:[0,1,1] neg_lo:[1,0,0] neg_hi:[1,0,0]
	v_pk_fma_f32 v[222:223], v[146:147], v[214:215], v[222:223] op_sel_hi:[0,1,1] neg_lo:[1,0,0] neg_hi:[1,0,0]
	v_pk_fma_f32 v[138:139], v[138:139], v[216:217], v[220:221]
	v_pk_fma_f32 v[140:141], v[140:141], v[218:219], v[222:223]
	s_waitcnt lgkmcnt(6)
	v_pk_mul_f32 v[144:145], v[138:139], v[230:231]
	v_pk_fma_f32 v[144:145], v[140:141], v[232:233], v[144:145]
	v_add_f32 v146, v144, v145
	ds_read_b128 v[186:189], v5 offset:7680
	ds_read_b128 v[190:193], v5 offset:7936
	ds_read_b128 v[194:197], v5 offset:8192
	ds_read_b128 v[198:201], v5 offset:8448
	ds_read_b128 v[202:205], v5 offset:8704
	ds_read_b32 v206, v9 offset:7680
	v_add_f32_dpp v146, v146, v146 quad_perm:[1,0,3,2] row_mask:0xf bank_mask:0xf bound_ctrl:1
	v_pk_mul_f32 v[224:225], v[138:139], v[224:225]
	v_pk_fma_f32 v[224:225], v[140:141], v[226:227], v[224:225]
	v_add_f32_dpp v146, v146, v146 quad_perm:[2,3,0,1] row_mask:0xf bank_mask:0xf bound_ctrl:1
	v_add_f32 v150, v224, v225
	v_pk_mul_f32 v[242:243], v[242:243], v[250:251] op_sel_hi:[1,0]
	v_add_f32_dpp v146, v146, v146 row_half_mirror row_mask:0xf bank_mask:0xf bound_ctrl:1
	v_pk_mul_f32 v[244:245], v[244:245], v[250:251] op_sel_hi:[1,0]
	s_nop 0
	v_add_f32_dpp v146, v146, v146 row_mirror row_mask:0xf bank_mask:0xf bound_ctrl:1
	v_pk_fma_f32 v[242:243], v[146:147], v[234:235], v[242:243] op_sel_hi:[0,1,1] neg_lo:[1,0,0] neg_hi:[1,0,0]
	v_pk_fma_f32 v[244:245], v[146:147], v[236:237], v[244:245] op_sel_hi:[0,1,1] neg_lo:[1,0,0] neg_hi:[1,0,0]
	v_pk_fma_f32 v[138:139], v[138:139], v[238:239], v[242:243]
	v_pk_fma_f32 v[140:141], v[140:141], v[240:241], v[244:245]
	s_waitcnt lgkmcnt(6)
	v_pk_mul_f32 v[144:145], v[138:139], v[164:165]
	v_pk_fma_f32 v[144:145], v[140:141], v[166:167], v[144:145]
	v_add_f32 v146, v144, v145
	ds_read_b128 v[208:211], v5 offset:9216
	ds_read_b128 v[212:215], v5 offset:9472
	ds_read_b128 v[216:219], v5 offset:9728
	ds_read_b128 v[220:223], v5 offset:9984
	ds_read_b128 v[224:227], v5 offset:10240
	ds_read_b32 v228, v9 offset:9216
	v_add_f32_dpp v146, v146, v146 quad_perm:[1,0,3,2] row_mask:0xf bank_mask:0xf bound_ctrl:1
	v_pk_mul_f32 v[246:247], v[138:139], v[246:247]
	v_pk_fma_f32 v[246:247], v[140:141], v[248:249], v[246:247]
	v_add_f32_dpp v146, v146, v146 quad_perm:[2,3,0,1] row_mask:0xf bank_mask:0xf bound_ctrl:1
	v_add_f32 v151, v246, v247
	v_pk_mul_f32 v[176:177], v[176:177], v[184:185] op_sel_hi:[1,0]
	v_add_f32_dpp v146, v146, v146 row_half_mirror row_mask:0xf bank_mask:0xf bound_ctrl:1
	v_pk_mul_f32 v[178:179], v[178:179], v[184:185] op_sel_hi:[1,0]
	s_nop 0
	v_add_f32_dpp v146, v146, v146 row_mirror row_mask:0xf bank_mask:0xf bound_ctrl:1
	v_pk_fma_f32 v[176:177], v[146:147], v[168:169], v[176:177] op_sel_hi:[0,1,1] neg_lo:[1,0,0] neg_hi:[1,0,0]
	v_pk_fma_f32 v[178:179], v[146:147], v[170:171], v[178:179] op_sel_hi:[0,1,1] neg_lo:[1,0,0] neg_hi:[1,0,0]
	v_pk_fma_f32 v[138:139], v[138:139], v[172:173], v[176:177]
	v_pk_fma_f32 v[140:141], v[140:141], v[174:175], v[178:179]
	s_waitcnt lgkmcnt(6)
	v_pk_mul_f32 v[144:145], v[138:139], v[186:187]
	v_pk_fma_f32 v[144:145], v[140:141], v[188:189], v[144:145]
	v_add_f32 v146, v144, v145
	ds_read_b128 v[230:233], v5 offset:10752
	ds_read_b128 v[234:237], v5 offset:11008
	ds_read_b128 v[238:241], v5 offset:11264
	ds_read_b128 v[242:245], v5 offset:11520
	ds_read_b128 v[246:249], v5 offset:11776
	ds_read_b32 v250, v9 offset:10752
	v_add_f32_dpp v146, v146, v146 quad_perm:[1,0,3,2] row_mask:0xf bank_mask:0xf bound_ctrl:1
	v_pk_mul_f32 v[180:181], v[138:139], v[180:181]
	v_pk_fma_f32 v[180:181], v[140:141], v[182:183], v[180:181]
	v_add_f32_dpp v146, v146, v146 quad_perm:[2,3,0,1] row_mask:0xf bank_mask:0xf bound_ctrl:1
	v_add_f32 v152, v180, v181
	v_pk_mul_f32 v[198:199], v[198:199], v[206:207] op_sel_hi:[1,0]
	v_add_f32_dpp v146, v146, v146 row_half_mirror row_mask:0xf bank_mask:0xf bound_ctrl:1
	v_pk_mul_f32 v[200:201], v[200:201], v[206:207] op_sel_hi:[1,0]
	s_nop 0
	v_add_f32_dpp v146, v146, v146 row_mirror row_mask:0xf bank_mask:0xf bound_ctrl:1
	v_pk_fma_f32 v[198:199], v[146:147], v[190:191], v[198:199] op_sel_hi:[0,1,1] neg_lo:[1,0,0] neg_hi:[1,0,0]
	v_pk_fma_f32 v[200:201], v[146:147], v[192:193], v[200:201] op_sel_hi:[0,1,1] neg_lo:[1,0,0] neg_hi:[1,0,0]
	v_pk_fma_f32 v[138:139], v[138:139], v[194:195], v[198:199]
	v_pk_fma_f32 v[140:141], v[140:141], v[196:197], v[200:201]
	s_waitcnt lgkmcnt(6)
	v_pk_mul_f32 v[144:145], v[138:139], v[208:209]
	v_pk_fma_f32 v[144:145], v[140:141], v[210:211], v[144:145]
	v_add_f32 v146, v144, v145
	ds_read_b128 v[164:167], v5 offset:12288
	ds_read_b128 v[168:171], v5 offset:12544
	ds_read_b128 v[172:175], v5 offset:12800
	ds_read_b128 v[176:179], v5 offset:13056
	ds_read_b128 v[180:183], v5 offset:13312
	ds_read_b32 v184, v9 offset:12288
	v_add_f32_dpp v146, v146, v146 quad_perm:[1,0,3,2] row_mask:0xf bank_mask:0xf bound_ctrl:1
	v_pk_mul_f32 v[202:203], v[138:139], v[202:203]
	v_pk_fma_f32 v[202:203], v[140:141], v[204:205], v[202:203]
	v_add_f32_dpp v146, v146, v146 quad_perm:[2,3,0,1] row_mask:0xf bank_mask:0xf bound_ctrl:1
	v_add_f32 v153, v202, v203
	v_pk_mul_f32 v[220:221], v[220:221], v[228:229] op_sel_hi:[1,0]
	v_add_f32_dpp v146, v146, v146 row_half_mirror row_mask:0xf bank_mask:0xf bound_ctrl:1
	v_pk_mul_f32 v[222:223], v[222:223], v[228:229] op_sel_hi:[1,0]
	s_nop 0
	v_add_f32_dpp v146, v146, v146 row_mirror row_mask:0xf bank_mask:0xf bound_ctrl:1
	v_pk_fma_f32 v[220:221], v[146:147], v[212:213], v[220:221] op_sel_hi:[0,1,1] neg_lo:[1,0,0] neg_hi:[1,0,0]
	v_pk_fma_f32 v[222:223], v[146:147], v[214:215], v[222:223] op_sel_hi:[0,1,1] neg_lo:[1,0,0] neg_hi:[1,0,0]
	v_pk_fma_f32 v[138:139], v[138:139], v[216:217], v[220:221]
	v_pk_fma_f32 v[140:141], v[140:141], v[218:219], v[222:223]
	s_waitcnt lgkmcnt(6)
	v_pk_mul_f32 v[144:145], v[138:139], v[230:231]
	v_pk_fma_f32 v[144:145], v[140:141], v[232:233], v[144:145]
	v_add_f32 v146, v144, v145
	ds_read_b128 v[186:189], v5 offset:13824
	ds_read_b128 v[190:193], v5 offset:14080
	ds_read_b128 v[194:197], v5 offset:14336
	ds_read_b128 v[198:201], v5 offset:14592
	ds_read_b128 v[202:205], v5 offset:14848
	ds_read_b32 v206, v9 offset:13824
	v_add_f32_dpp v146, v146, v146 quad_perm:[1,0,3,2] row_mask:0xf bank_mask:0xf bound_ctrl:1
	v_pk_mul_f32 v[224:225], v[138:139], v[224:225]
	v_pk_fma_f32 v[224:225], v[140:141], v[226:227], v[224:225]
	v_add_f32_dpp v146, v146, v146 quad_perm:[2,3,0,1] row_mask:0xf bank_mask:0xf bound_ctrl:1
	v_add_f32 v154, v224, v225
	v_pk_mul_f32 v[242:243], v[242:243], v[250:251] op_sel_hi:[1,0]
	v_add_f32_dpp v146, v146, v146 row_half_mirror row_mask:0xf bank_mask:0xf bound_ctrl:1
	v_pk_mul_f32 v[244:245], v[244:245], v[250:251] op_sel_hi:[1,0]
	s_nop 0
	v_add_f32_dpp v146, v146, v146 row_mirror row_mask:0xf bank_mask:0xf bound_ctrl:1
	v_pk_fma_f32 v[242:243], v[146:147], v[234:235], v[242:243] op_sel_hi:[0,1,1] neg_lo:[1,0,0] neg_hi:[1,0,0]
	v_pk_fma_f32 v[244:245], v[146:147], v[236:237], v[244:245] op_sel_hi:[0,1,1] neg_lo:[1,0,0] neg_hi:[1,0,0]
	v_pk_fma_f32 v[138:139], v[138:139], v[238:239], v[242:243]
	v_pk_fma_f32 v[140:141], v[140:141], v[240:241], v[244:245]
	s_waitcnt lgkmcnt(6)
	v_pk_mul_f32 v[144:145], v[138:139], v[164:165]
	v_pk_fma_f32 v[144:145], v[140:141], v[166:167], v[144:145]
	v_add_f32 v146, v144, v145
	ds_read_b128 v[208:211], v5 offset:15360
	ds_read_b128 v[212:215], v5 offset:15616
	ds_read_b128 v[216:219], v5 offset:15872
	ds_read_b128 v[220:223], v5 offset:16128
	ds_read_b128 v[224:227], v5 offset:16384
	ds_read_b32 v228, v9 offset:15360
	v_add_f32_dpp v146, v146, v146 quad_perm:[1,0,3,2] row_mask:0xf bank_mask:0xf bound_ctrl:1
	v_pk_mul_f32 v[246:247], v[138:139], v[246:247]
	v_pk_fma_f32 v[246:247], v[140:141], v[248:249], v[246:247]
	v_add_f32_dpp v146, v146, v146 quad_perm:[2,3,0,1] row_mask:0xf bank_mask:0xf bound_ctrl:1
	v_add_f32 v155, v246, v247
	v_pk_mul_f32 v[176:177], v[176:177], v[184:185] op_sel_hi:[1,0]
	v_add_f32_dpp v146, v146, v146 row_half_mirror row_mask:0xf bank_mask:0xf bound_ctrl:1
	v_pk_mul_f32 v[178:179], v[178:179], v[184:185] op_sel_hi:[1,0]
	s_nop 0
	v_add_f32_dpp v146, v146, v146 row_mirror row_mask:0xf bank_mask:0xf bound_ctrl:1
	v_pk_fma_f32 v[176:177], v[146:147], v[168:169], v[176:177] op_sel_hi:[0,1,1] neg_lo:[1,0,0] neg_hi:[1,0,0]
	v_pk_fma_f32 v[178:179], v[146:147], v[170:171], v[178:179] op_sel_hi:[0,1,1] neg_lo:[1,0,0] neg_hi:[1,0,0]
	v_pk_fma_f32 v[138:139], v[138:139], v[172:173], v[176:177]
	v_pk_fma_f32 v[140:141], v[140:141], v[174:175], v[178:179]
	s_waitcnt lgkmcnt(6)
	v_pk_mul_f32 v[144:145], v[138:139], v[186:187]
	v_pk_fma_f32 v[144:145], v[140:141], v[188:189], v[144:145]
	v_add_f32 v146, v144, v145
	ds_read_b128 v[230:233], v5 offset:16896
	ds_read_b128 v[234:237], v5 offset:17152
	ds_read_b128 v[238:241], v5 offset:17408
	ds_read_b128 v[242:245], v5 offset:17664
	ds_read_b128 v[246:249], v5 offset:17920
	ds_read_b32 v250, v9 offset:16896
	v_add_f32_dpp v146, v146, v146 quad_perm:[1,0,3,2] row_mask:0xf bank_mask:0xf bound_ctrl:1
	v_pk_mul_f32 v[180:181], v[138:139], v[180:181]
	v_pk_fma_f32 v[180:181], v[140:141], v[182:183], v[180:181]
	v_add_f32_dpp v146, v146, v146 quad_perm:[2,3,0,1] row_mask:0xf bank_mask:0xf bound_ctrl:1
	v_add_f32 v156, v180, v181
	v_pk_mul_f32 v[198:199], v[198:199], v[206:207] op_sel_hi:[1,0]
	v_add_f32_dpp v146, v146, v146 row_half_mirror row_mask:0xf bank_mask:0xf bound_ctrl:1
	v_pk_mul_f32 v[200:201], v[200:201], v[206:207] op_sel_hi:[1,0]
	s_nop 0
	v_add_f32_dpp v146, v146, v146 row_mirror row_mask:0xf bank_mask:0xf bound_ctrl:1
	v_pk_fma_f32 v[198:199], v[146:147], v[190:191], v[198:199] op_sel_hi:[0,1,1] neg_lo:[1,0,0] neg_hi:[1,0,0]
	v_pk_fma_f32 v[200:201], v[146:147], v[192:193], v[200:201] op_sel_hi:[0,1,1] neg_lo:[1,0,0] neg_hi:[1,0,0]
	v_pk_fma_f32 v[138:139], v[138:139], v[194:195], v[198:199]
	v_pk_fma_f32 v[140:141], v[140:141], v[196:197], v[200:201]
	s_waitcnt lgkmcnt(6)
	v_pk_mul_f32 v[144:145], v[138:139], v[208:209]
	v_pk_fma_f32 v[144:145], v[140:141], v[210:211], v[144:145]
	v_add_f32 v146, v144, v145
	ds_read_b128 v[164:167], v5 offset:18432
	ds_read_b128 v[168:171], v5 offset:18688
	ds_read_b128 v[172:175], v5 offset:18944
	ds_read_b128 v[176:179], v5 offset:19200
	ds_read_b128 v[180:183], v5 offset:19456
	ds_read_b32 v184, v9 offset:18432
	v_add_f32_dpp v146, v146, v146 quad_perm:[1,0,3,2] row_mask:0xf bank_mask:0xf bound_ctrl:1
	v_pk_mul_f32 v[202:203], v[138:139], v[202:203]
	v_pk_fma_f32 v[202:203], v[140:141], v[204:205], v[202:203]
	v_add_f32_dpp v146, v146, v146 quad_perm:[2,3,0,1] row_mask:0xf bank_mask:0xf bound_ctrl:1
	v_add_f32 v157, v202, v203
	v_pk_mul_f32 v[220:221], v[220:221], v[228:229] op_sel_hi:[1,0]
	v_add_f32_dpp v146, v146, v146 row_half_mirror row_mask:0xf bank_mask:0xf bound_ctrl:1
	v_pk_mul_f32 v[222:223], v[222:223], v[228:229] op_sel_hi:[1,0]
	s_nop 0
	v_add_f32_dpp v146, v146, v146 row_mirror row_mask:0xf bank_mask:0xf bound_ctrl:1
	v_pk_fma_f32 v[220:221], v[146:147], v[212:213], v[220:221] op_sel_hi:[0,1,1] neg_lo:[1,0,0] neg_hi:[1,0,0]
	v_pk_fma_f32 v[222:223], v[146:147], v[214:215], v[222:223] op_sel_hi:[0,1,1] neg_lo:[1,0,0] neg_hi:[1,0,0]
	v_pk_fma_f32 v[138:139], v[138:139], v[216:217], v[220:221]
	v_pk_fma_f32 v[140:141], v[140:141], v[218:219], v[222:223]
	s_waitcnt lgkmcnt(6)
	v_pk_mul_f32 v[144:145], v[138:139], v[230:231]
	v_pk_fma_f32 v[144:145], v[140:141], v[232:233], v[144:145]
	v_add_f32 v146, v144, v145
	ds_read_b128 v[186:189], v5 offset:19968
	ds_read_b128 v[190:193], v5 offset:20224
	ds_read_b128 v[194:197], v5 offset:20480
	ds_read_b128 v[198:201], v5 offset:20736
	ds_read_b128 v[202:205], v5 offset:20992
	ds_read_b32 v206, v9 offset:19968
	v_add_f32_dpp v146, v146, v146 quad_perm:[1,0,3,2] row_mask:0xf bank_mask:0xf bound_ctrl:1
	v_pk_mul_f32 v[224:225], v[138:139], v[224:225]
	v_pk_fma_f32 v[224:225], v[140:141], v[226:227], v[224:225]
	v_add_f32_dpp v146, v146, v146 quad_perm:[2,3,0,1] row_mask:0xf bank_mask:0xf bound_ctrl:1
	v_add_f32 v158, v224, v225
	v_pk_mul_f32 v[242:243], v[242:243], v[250:251] op_sel_hi:[1,0]
	v_add_f32_dpp v146, v146, v146 row_half_mirror row_mask:0xf bank_mask:0xf bound_ctrl:1
	v_pk_mul_f32 v[244:245], v[244:245], v[250:251] op_sel_hi:[1,0]
	s_nop 0
	v_add_f32_dpp v146, v146, v146 row_mirror row_mask:0xf bank_mask:0xf bound_ctrl:1
	v_pk_fma_f32 v[242:243], v[146:147], v[234:235], v[242:243] op_sel_hi:[0,1,1] neg_lo:[1,0,0] neg_hi:[1,0,0]
	v_pk_fma_f32 v[244:245], v[146:147], v[236:237], v[244:245] op_sel_hi:[0,1,1] neg_lo:[1,0,0] neg_hi:[1,0,0]
	v_pk_fma_f32 v[138:139], v[138:139], v[238:239], v[242:243]
	v_pk_fma_f32 v[140:141], v[140:141], v[240:241], v[244:245]
	s_waitcnt lgkmcnt(6)
	v_pk_mul_f32 v[144:145], v[138:139], v[164:165]
	v_pk_fma_f32 v[144:145], v[140:141], v[166:167], v[144:145]
	v_add_f32 v146, v144, v145
	ds_read_b128 v[208:211], v5 offset:21504
	ds_read_b128 v[212:215], v5 offset:21760
	ds_read_b128 v[216:219], v5 offset:22016
	ds_read_b128 v[220:223], v5 offset:22272
	ds_read_b128 v[224:227], v5 offset:22528
	ds_read_b32 v228, v9 offset:21504
	v_add_f32_dpp v146, v146, v146 quad_perm:[1,0,3,2] row_mask:0xf bank_mask:0xf bound_ctrl:1
	v_pk_mul_f32 v[246:247], v[138:139], v[246:247]
	v_pk_fma_f32 v[246:247], v[140:141], v[248:249], v[246:247]
	v_add_f32_dpp v146, v146, v146 quad_perm:[2,3,0,1] row_mask:0xf bank_mask:0xf bound_ctrl:1
	v_add_f32 v159, v246, v247
	v_pk_mul_f32 v[176:177], v[176:177], v[184:185] op_sel_hi:[1,0]
	v_add_f32_dpp v146, v146, v146 row_half_mirror row_mask:0xf bank_mask:0xf bound_ctrl:1
	v_pk_mul_f32 v[178:179], v[178:179], v[184:185] op_sel_hi:[1,0]
	s_nop 0
	v_add_f32_dpp v146, v146, v146 row_mirror row_mask:0xf bank_mask:0xf bound_ctrl:1
	v_pk_fma_f32 v[176:177], v[146:147], v[168:169], v[176:177] op_sel_hi:[0,1,1] neg_lo:[1,0,0] neg_hi:[1,0,0]
	v_pk_fma_f32 v[178:179], v[146:147], v[170:171], v[178:179] op_sel_hi:[0,1,1] neg_lo:[1,0,0] neg_hi:[1,0,0]
	v_pk_fma_f32 v[138:139], v[138:139], v[172:173], v[176:177]
	v_pk_fma_f32 v[140:141], v[140:141], v[174:175], v[178:179]
	s_waitcnt lgkmcnt(6)
	v_pk_mul_f32 v[144:145], v[138:139], v[186:187]
	v_pk_fma_f32 v[144:145], v[140:141], v[188:189], v[144:145]
	v_add_f32 v146, v144, v145
	ds_read_b128 v[230:233], v5 offset:23040
	ds_read_b128 v[234:237], v5 offset:23296
	ds_read_b128 v[238:241], v5 offset:23552
	ds_read_b128 v[242:245], v5 offset:23808
	ds_read_b128 v[246:249], v5 offset:24064
	ds_read_b32 v250, v9 offset:23040
	v_add_f32_dpp v146, v146, v146 quad_perm:[1,0,3,2] row_mask:0xf bank_mask:0xf bound_ctrl:1
	v_pk_mul_f32 v[180:181], v[138:139], v[180:181]
	v_pk_fma_f32 v[180:181], v[140:141], v[182:183], v[180:181]
	v_add_f32_dpp v146, v146, v146 quad_perm:[2,3,0,1] row_mask:0xf bank_mask:0xf bound_ctrl:1
	v_add_f32 v160, v180, v181
	v_pk_mul_f32 v[198:199], v[198:199], v[206:207] op_sel_hi:[1,0]
	v_add_f32_dpp v146, v146, v146 row_half_mirror row_mask:0xf bank_mask:0xf bound_ctrl:1
	v_pk_mul_f32 v[200:201], v[200:201], v[206:207] op_sel_hi:[1,0]
	s_nop 0
	v_add_f32_dpp v146, v146, v146 row_mirror row_mask:0xf bank_mask:0xf bound_ctrl:1
	v_pk_fma_f32 v[198:199], v[146:147], v[190:191], v[198:199] op_sel_hi:[0,1,1] neg_lo:[1,0,0] neg_hi:[1,0,0]
	v_pk_fma_f32 v[200:201], v[146:147], v[192:193], v[200:201] op_sel_hi:[0,1,1] neg_lo:[1,0,0] neg_hi:[1,0,0]
	v_pk_fma_f32 v[138:139], v[138:139], v[194:195], v[198:199]
	v_pk_fma_f32 v[140:141], v[140:141], v[196:197], v[200:201]
	s_waitcnt lgkmcnt(6)
	v_pk_mul_f32 v[144:145], v[138:139], v[208:209]
	v_pk_fma_f32 v[144:145], v[140:141], v[210:211], v[144:145]
	v_add_f32 v146, v144, v145
	ds_read_b128 v[164:167], v5 offset:24576
	ds_read_b128 v[168:171], v5 offset:24832
	ds_read_b128 v[172:175], v5 offset:25088
	ds_read_b128 v[176:179], v5 offset:25344
	ds_read_b128 v[180:183], v5 offset:25600
	ds_read_b32 v184, v9 offset:24576
	v_add_f32_dpp v146, v146, v146 quad_perm:[1,0,3,2] row_mask:0xf bank_mask:0xf bound_ctrl:1
	v_pk_mul_f32 v[202:203], v[138:139], v[202:203]
	v_pk_fma_f32 v[202:203], v[140:141], v[204:205], v[202:203]
	v_add_f32_dpp v146, v146, v146 quad_perm:[2,3,0,1] row_mask:0xf bank_mask:0xf bound_ctrl:1
	v_add_f32 v161, v202, v203
	v_pk_mul_f32 v[220:221], v[220:221], v[228:229] op_sel_hi:[1,0]
	v_add_f32_dpp v146, v146, v146 row_half_mirror row_mask:0xf bank_mask:0xf bound_ctrl:1
	v_pk_mul_f32 v[222:223], v[222:223], v[228:229] op_sel_hi:[1,0]
	s_nop 0
	v_add_f32_dpp v146, v146, v146 row_mirror row_mask:0xf bank_mask:0xf bound_ctrl:1
	v_pk_fma_f32 v[220:221], v[146:147], v[212:213], v[220:221] op_sel_hi:[0,1,1] neg_lo:[1,0,0] neg_hi:[1,0,0]
	v_pk_fma_f32 v[222:223], v[146:147], v[214:215], v[222:223] op_sel_hi:[0,1,1] neg_lo:[1,0,0] neg_hi:[1,0,0]
	v_pk_fma_f32 v[138:139], v[138:139], v[216:217], v[220:221]
	v_pk_fma_f32 v[140:141], v[140:141], v[218:219], v[222:223]
	s_waitcnt lgkmcnt(6)
	v_pk_mul_f32 v[144:145], v[138:139], v[230:231]
	v_pk_fma_f32 v[144:145], v[140:141], v[232:233], v[144:145]
	v_add_f32 v146, v144, v145
	ds_read_b128 v[186:189], v5 offset:26112
	ds_read_b128 v[190:193], v5 offset:26368
	ds_read_b128 v[194:197], v5 offset:26624
	ds_read_b128 v[198:201], v5 offset:26880
	ds_read_b128 v[202:205], v5 offset:27136
	ds_read_b32 v206, v9 offset:26112
	v_add_f32_dpp v146, v146, v146 quad_perm:[1,0,3,2] row_mask:0xf bank_mask:0xf bound_ctrl:1
	v_pk_mul_f32 v[224:225], v[138:139], v[224:225]
	v_pk_fma_f32 v[224:225], v[140:141], v[226:227], v[224:225]
	v_add_f32_dpp v146, v146, v146 quad_perm:[2,3,0,1] row_mask:0xf bank_mask:0xf bound_ctrl:1
	v_add_f32 v162, v224, v225
	v_pk_mul_f32 v[242:243], v[242:243], v[250:251] op_sel_hi:[1,0]
	v_add_f32_dpp v146, v146, v146 row_half_mirror row_mask:0xf bank_mask:0xf bound_ctrl:1
	v_pk_mul_f32 v[244:245], v[244:245], v[250:251] op_sel_hi:[1,0]
	s_nop 0
	v_add_f32_dpp v146, v146, v146 row_mirror row_mask:0xf bank_mask:0xf bound_ctrl:1
	v_pk_fma_f32 v[242:243], v[146:147], v[234:235], v[242:243] op_sel_hi:[0,1,1] neg_lo:[1,0,0] neg_hi:[1,0,0]
	v_pk_fma_f32 v[244:245], v[146:147], v[236:237], v[244:245] op_sel_hi:[0,1,1] neg_lo:[1,0,0] neg_hi:[1,0,0]
	v_pk_fma_f32 v[138:139], v[138:139], v[238:239], v[242:243]
	v_pk_fma_f32 v[140:141], v[140:141], v[240:241], v[244:245]
	s_waitcnt lgkmcnt(6)
	v_pk_mul_f32 v[144:145], v[138:139], v[164:165]
	v_pk_fma_f32 v[144:145], v[140:141], v[166:167], v[144:145]
	v_add_f32 v146, v144, v145
	ds_read_b128 v[208:211], v5 offset:27648
	ds_read_b128 v[212:215], v5 offset:27904
	ds_read_b128 v[216:219], v5 offset:28160
	ds_read_b128 v[220:223], v5 offset:28416
	ds_read_b128 v[224:227], v5 offset:28672
	ds_read_b32 v228, v9 offset:27648
	v_add_f32_dpp v146, v146, v146 quad_perm:[1,0,3,2] row_mask:0xf bank_mask:0xf bound_ctrl:1
	v_pk_mul_f32 v[246:247], v[138:139], v[246:247]
	v_pk_fma_f32 v[246:247], v[140:141], v[248:249], v[246:247]
	v_add_f32_dpp v146, v146, v146 quad_perm:[2,3,0,1] row_mask:0xf bank_mask:0xf bound_ctrl:1
	v_add_f32 v163, v246, v247
	v_pk_mul_f32 v[176:177], v[176:177], v[184:185] op_sel_hi:[1,0]
	v_add_f32_dpp v146, v146, v146 row_half_mirror row_mask:0xf bank_mask:0xf bound_ctrl:1
	v_pk_mul_f32 v[178:179], v[178:179], v[184:185] op_sel_hi:[1,0]
	s_nop 0
	v_add_f32_dpp v146, v146, v146 row_mirror row_mask:0xf bank_mask:0xf bound_ctrl:1
	v_pk_fma_f32 v[176:177], v[146:147], v[168:169], v[176:177] op_sel_hi:[0,1,1] neg_lo:[1,0,0] neg_hi:[1,0,0]
	v_pk_fma_f32 v[178:179], v[146:147], v[170:171], v[178:179] op_sel_hi:[0,1,1] neg_lo:[1,0,0] neg_hi:[1,0,0]
	v_pk_fma_f32 v[138:139], v[138:139], v[172:173], v[176:177]
	v_pk_fma_f32 v[140:141], v[140:141], v[174:175], v[178:179]
	s_waitcnt lgkmcnt(6)
	v_pk_mul_f32 v[144:145], v[138:139], v[186:187]
	v_pk_fma_f32 v[144:145], v[140:141], v[188:189], v[144:145]
	v_add_f32 v146, v144, v145
	v_add_f32_dpp v230, v148, v148 row_mirror row_mask:0xf bank_mask:0x3 bound_ctrl:1
	v_add_f32_dpp v230, v156, v156 row_mirror row_mask:0xf bank_mask:0xc bound_ctrl:1
	v_add_f32_dpp v231, v149, v149 row_mirror row_mask:0xf bank_mask:0x3 bound_ctrl:1
	v_add_f32_dpp v231, v157, v157 row_mirror row_mask:0xf bank_mask:0xc bound_ctrl:1
	v_add_f32_dpp v232, v150, v150 row_mirror row_mask:0xf bank_mask:0x3 bound_ctrl:1
	v_add_f32_dpp v232, v158, v158 row_mirror row_mask:0xf bank_mask:0xc bound_ctrl:1
	v_add_f32_dpp v233, v151, v151 row_mirror row_mask:0xf bank_mask:0x3 bound_ctrl:1
	v_add_f32_dpp v233, v159, v159 row_mirror row_mask:0xf bank_mask:0xc bound_ctrl:1
	v_add_f32_dpp v234, v152, v152 row_mirror row_mask:0xf bank_mask:0x3 bound_ctrl:1
	v_add_f32_dpp v234, v160, v160 row_mirror row_mask:0xf bank_mask:0xc bound_ctrl:1
	v_add_f32_dpp v235, v153, v153 row_mirror row_mask:0xf bank_mask:0x3 bound_ctrl:1
	v_add_f32_dpp v235, v161, v161 row_mirror row_mask:0xf bank_mask:0xc bound_ctrl:1
	v_add_f32_dpp v236, v154, v154 row_mirror row_mask:0xf bank_mask:0x3 bound_ctrl:1
	v_add_f32_dpp v236, v162, v162 row_mirror row_mask:0xf bank_mask:0xc bound_ctrl:1
	v_add_f32_dpp v237, v155, v155 row_mirror row_mask:0xf bank_mask:0x3 bound_ctrl:1
	v_add_f32_dpp v237, v163, v163 row_mirror row_mask:0xf bank_mask:0xc bound_ctrl:1
	v_add_f32_dpp v238, v230, v230 row_half_mirror row_mask:0xf bank_mask:0x5 bound_ctrl:1
	v_add_f32_dpp v238, v234, v234 row_half_mirror row_mask:0xf bank_mask:0xa bound_ctrl:1
	v_add_f32_dpp v239, v231, v231 row_half_mirror row_mask:0xf bank_mask:0x5 bound_ctrl:1
	v_add_f32_dpp v239, v235, v235 row_half_mirror row_mask:0xf bank_mask:0xa bound_ctrl:1
	v_add_f32_dpp v240, v232, v232 row_half_mirror row_mask:0xf bank_mask:0x5 bound_ctrl:1
	v_add_f32_dpp v240, v236, v236 row_half_mirror row_mask:0xf bank_mask:0xa bound_ctrl:1
	v_add_f32_dpp v241, v233, v233 row_half_mirror row_mask:0xf bank_mask:0x5 bound_ctrl:1
	v_add_f32_dpp v241, v237, v237 row_half_mirror row_mask:0xf bank_mask:0xa bound_ctrl:1
	s_mov_b32 vcc_lo, 0xcccccccc
	s_mov_b32 vcc_hi, 0xcccccccc
	v_cndmask_b32 v244, v240, v238, vcc
	v_cndmask_b32 v245, v241, v239, vcc
	v_cndmask_b32 v242, v238, v240, vcc
	v_cndmask_b32 v243, v239, v241, vcc
	v_add_f32_dpp v242, v244, v242 quad_perm:[2,3,0,1] row_mask:0xf bank_mask:0xf bound_ctrl:1
	v_add_f32_dpp v243, v245, v243 quad_perm:[2,3,0,1] row_mask:0xf bank_mask:0xf bound_ctrl:1
	s_mov_b32 vcc_lo, 0xaaaaaaaa
	s_mov_b32 vcc_hi, 0xaaaaaaaa
	v_cndmask_b32 v244, v243, v242, vcc
	v_cndmask_b32 v245, v242, v243, vcc
	s_nop 0
	v_add_f32_dpp v18, v244, v245 quad_perm:[1,0,3,2] row_mask:0xf bank_mask:0xf bound_ctrl:1
	ds_read_b128 v[230:233], v5 offset:29184
	ds_read_b128 v[234:237], v5 offset:29440
	ds_read_b128 v[238:241], v5 offset:29696
	ds_read_b128 v[242:245], v5 offset:29952
	ds_read_b128 v[246:249], v5 offset:30208
	ds_read_b32 v250, v9 offset:29184
	v_add_f32_dpp v146, v146, v146 quad_perm:[1,0,3,2] row_mask:0xf bank_mask:0xf bound_ctrl:1
	v_pk_mul_f32 v[180:181], v[138:139], v[180:181]
	v_pk_fma_f32 v[180:181], v[140:141], v[182:183], v[180:181]
	v_add_f32_dpp v146, v146, v146 quad_perm:[2,3,0,1] row_mask:0xf bank_mask:0xf bound_ctrl:1
	v_add_f32 v148, v180, v181
	v_pk_mul_f32 v[198:199], v[198:199], v[206:207] op_sel_hi:[1,0]
	v_add_f32_dpp v146, v146, v146 row_half_mirror row_mask:0xf bank_mask:0xf bound_ctrl:1
	v_pk_mul_f32 v[200:201], v[200:201], v[206:207] op_sel_hi:[1,0]
	s_nop 0
	v_add_f32_dpp v146, v146, v146 row_mirror row_mask:0xf bank_mask:0xf bound_ctrl:1
	v_pk_fma_f32 v[198:199], v[146:147], v[190:191], v[198:199] op_sel_hi:[0,1,1] neg_lo:[1,0,0] neg_hi:[1,0,0]
	v_pk_fma_f32 v[200:201], v[146:147], v[192:193], v[200:201] op_sel_hi:[0,1,1] neg_lo:[1,0,0] neg_hi:[1,0,0]
	v_pk_fma_f32 v[138:139], v[138:139], v[194:195], v[198:199]
	v_pk_fma_f32 v[140:141], v[140:141], v[196:197], v[200:201]
	s_waitcnt lgkmcnt(6)
	v_pk_mul_f32 v[144:145], v[138:139], v[208:209]
	v_pk_fma_f32 v[144:145], v[140:141], v[210:211], v[144:145]
	v_add_f32 v146, v144, v145
	ds_read_b128 v[164:167], v5 offset:30720
	ds_read_b128 v[168:171], v5 offset:30976
	ds_read_b128 v[172:175], v5 offset:31232
	ds_read_b128 v[176:179], v5 offset:31488
	ds_read_b128 v[180:183], v5 offset:31744
	ds_read_b32 v184, v9 offset:30720
	v_add_f32_dpp v146, v146, v146 quad_perm:[1,0,3,2] row_mask:0xf bank_mask:0xf bound_ctrl:1
	v_pk_mul_f32 v[202:203], v[138:139], v[202:203]
	v_pk_fma_f32 v[202:203], v[140:141], v[204:205], v[202:203]
	v_add_f32_dpp v146, v146, v146 quad_perm:[2,3,0,1] row_mask:0xf bank_mask:0xf bound_ctrl:1
	v_add_f32 v149, v202, v203
	v_pk_mul_f32 v[220:221], v[220:221], v[228:229] op_sel_hi:[1,0]
	v_add_f32_dpp v146, v146, v146 row_half_mirror row_mask:0xf bank_mask:0xf bound_ctrl:1
	v_pk_mul_f32 v[222:223], v[222:223], v[228:229] op_sel_hi:[1,0]
	s_nop 0
	v_add_f32_dpp v146, v146, v146 row_mirror row_mask:0xf bank_mask:0xf bound_ctrl:1
	v_pk_fma_f32 v[220:221], v[146:147], v[212:213], v[220:221] op_sel_hi:[0,1,1] neg_lo:[1,0,0] neg_hi:[1,0,0]
	v_pk_fma_f32 v[222:223], v[146:147], v[214:215], v[222:223] op_sel_hi:[0,1,1] neg_lo:[1,0,0] neg_hi:[1,0,0]
	v_pk_fma_f32 v[138:139], v[138:139], v[216:217], v[220:221]
	v_pk_fma_f32 v[140:141], v[140:141], v[218:219], v[222:223]
	s_waitcnt lgkmcnt(6)
	v_pk_mul_f32 v[144:145], v[138:139], v[230:231]
	v_pk_fma_f32 v[144:145], v[140:141], v[232:233], v[144:145]
	v_add_f32 v146, v144, v145
	ds_read_b128 v[186:189], v5 offset:32256
	ds_read_b128 v[190:193], v5 offset:32512
	ds_read_b128 v[194:197], v5 offset:32768
	ds_read_b128 v[198:201], v5 offset:33024
	ds_read_b128 v[202:205], v5 offset:33280
	ds_read_b32 v206, v9 offset:32256
	v_add_f32_dpp v146, v146, v146 quad_perm:[1,0,3,2] row_mask:0xf bank_mask:0xf bound_ctrl:1
	v_pk_mul_f32 v[224:225], v[138:139], v[224:225]
	v_pk_fma_f32 v[224:225], v[140:141], v[226:227], v[224:225]
	v_add_f32_dpp v146, v146, v146 quad_perm:[2,3,0,1] row_mask:0xf bank_mask:0xf bound_ctrl:1
	v_add_f32 v150, v224, v225
	v_pk_mul_f32 v[242:243], v[242:243], v[250:251] op_sel_hi:[1,0]
	v_add_f32_dpp v146, v146, v146 row_half_mirror row_mask:0xf bank_mask:0xf bound_ctrl:1
	v_pk_mul_f32 v[244:245], v[244:245], v[250:251] op_sel_hi:[1,0]
	s_nop 0
	v_add_f32_dpp v146, v146, v146 row_mirror row_mask:0xf bank_mask:0xf bound_ctrl:1
	v_pk_fma_f32 v[242:243], v[146:147], v[234:235], v[242:243] op_sel_hi:[0,1,1] neg_lo:[1,0,0] neg_hi:[1,0,0]
	v_pk_fma_f32 v[244:245], v[146:147], v[236:237], v[244:245] op_sel_hi:[0,1,1] neg_lo:[1,0,0] neg_hi:[1,0,0]
	v_pk_fma_f32 v[138:139], v[138:139], v[238:239], v[242:243]
	v_pk_fma_f32 v[140:141], v[140:141], v[240:241], v[244:245]
	s_waitcnt lgkmcnt(6)
	v_pk_mul_f32 v[144:145], v[138:139], v[164:165]
	v_pk_fma_f32 v[144:145], v[140:141], v[166:167], v[144:145]
	v_add_f32 v146, v144, v145
	ds_read_b128 v[208:211], v5 offset:33792
	ds_read_b128 v[212:215], v5 offset:34048
	ds_read_b128 v[216:219], v5 offset:34304
	ds_read_b128 v[220:223], v5 offset:34560
	ds_read_b128 v[224:227], v5 offset:34816
	ds_read_b32 v228, v9 offset:33792
	v_add_f32_dpp v146, v146, v146 quad_perm:[1,0,3,2] row_mask:0xf bank_mask:0xf bound_ctrl:1
	v_pk_mul_f32 v[246:247], v[138:139], v[246:247]
	v_pk_fma_f32 v[246:247], v[140:141], v[248:249], v[246:247]
	v_add_f32_dpp v146, v146, v146 quad_perm:[2,3,0,1] row_mask:0xf bank_mask:0xf bound_ctrl:1
	v_add_f32 v151, v246, v247
	v_pk_mul_f32 v[176:177], v[176:177], v[184:185] op_sel_hi:[1,0]
	v_add_f32_dpp v146, v146, v146 row_half_mirror row_mask:0xf bank_mask:0xf bound_ctrl:1
	v_pk_mul_f32 v[178:179], v[178:179], v[184:185] op_sel_hi:[1,0]
	s_nop 0
	v_add_f32_dpp v146, v146, v146 row_mirror row_mask:0xf bank_mask:0xf bound_ctrl:1
	v_pk_fma_f32 v[176:177], v[146:147], v[168:169], v[176:177] op_sel_hi:[0,1,1] neg_lo:[1,0,0] neg_hi:[1,0,0]
	v_pk_fma_f32 v[178:179], v[146:147], v[170:171], v[178:179] op_sel_hi:[0,1,1] neg_lo:[1,0,0] neg_hi:[1,0,0]
	v_pk_fma_f32 v[138:139], v[138:139], v[172:173], v[176:177]
	v_pk_fma_f32 v[140:141], v[140:141], v[174:175], v[178:179]
	s_waitcnt lgkmcnt(6)
	v_pk_mul_f32 v[144:145], v[138:139], v[186:187]
	v_pk_fma_f32 v[144:145], v[140:141], v[188:189], v[144:145]
	v_add_f32 v146, v144, v145
	ds_read_b128 v[230:233], v5 offset:35328
	ds_read_b128 v[234:237], v5 offset:35584
	ds_read_b128 v[238:241], v5 offset:35840
	ds_read_b128 v[242:245], v5 offset:36096
	ds_read_b128 v[246:249], v5 offset:36352
	ds_read_b32 v250, v9 offset:35328
	v_add_f32_dpp v146, v146, v146 quad_perm:[1,0,3,2] row_mask:0xf bank_mask:0xf bound_ctrl:1
	v_pk_mul_f32 v[180:181], v[138:139], v[180:181]
	v_pk_fma_f32 v[180:181], v[140:141], v[182:183], v[180:181]
	v_add_f32_dpp v146, v146, v146 quad_perm:[2,3,0,1] row_mask:0xf bank_mask:0xf bound_ctrl:1
	v_add_f32 v152, v180, v181
	v_pk_mul_f32 v[198:199], v[198:199], v[206:207] op_sel_hi:[1,0]
	v_add_f32_dpp v146, v146, v146 row_half_mirror row_mask:0xf bank_mask:0xf bound_ctrl:1
	v_pk_mul_f32 v[200:201], v[200:201], v[206:207] op_sel_hi:[1,0]
	s_nop 0
	v_add_f32_dpp v146, v146, v146 row_mirror row_mask:0xf bank_mask:0xf bound_ctrl:1
	v_pk_fma_f32 v[198:199], v[146:147], v[190:191], v[198:199] op_sel_hi:[0,1,1] neg_lo:[1,0,0] neg_hi:[1,0,0]
	v_pk_fma_f32 v[200:201], v[146:147], v[192:193], v[200:201] op_sel_hi:[0,1,1] neg_lo:[1,0,0] neg_hi:[1,0,0]
	v_pk_fma_f32 v[138:139], v[138:139], v[194:195], v[198:199]
	v_pk_fma_f32 v[140:141], v[140:141], v[196:197], v[200:201]
	s_waitcnt lgkmcnt(6)
	v_pk_mul_f32 v[144:145], v[138:139], v[208:209]
	v_pk_fma_f32 v[144:145], v[140:141], v[210:211], v[144:145]
	v_add_f32 v146, v144, v145
	ds_read_b128 v[164:167], v5 offset:36864
	ds_read_b128 v[168:171], v5 offset:37120
	ds_read_b128 v[172:175], v5 offset:37376
	ds_read_b128 v[176:179], v5 offset:37632
	ds_read_b128 v[180:183], v5 offset:37888
	ds_read_b32 v184, v9 offset:36864
	v_add_f32_dpp v146, v146, v146 quad_perm:[1,0,3,2] row_mask:0xf bank_mask:0xf bound_ctrl:1
	v_pk_mul_f32 v[202:203], v[138:139], v[202:203]
	v_pk_fma_f32 v[202:203], v[140:141], v[204:205], v[202:203]
	v_add_f32_dpp v146, v146, v146 quad_perm:[2,3,0,1] row_mask:0xf bank_mask:0xf bound_ctrl:1
	v_add_f32 v153, v202, v203
	v_pk_mul_f32 v[220:221], v[220:221], v[228:229] op_sel_hi:[1,0]
	v_add_f32_dpp v146, v146, v146 row_half_mirror row_mask:0xf bank_mask:0xf bound_ctrl:1
	v_pk_mul_f32 v[222:223], v[222:223], v[228:229] op_sel_hi:[1,0]
	s_nop 0
	v_add_f32_dpp v146, v146, v146 row_mirror row_mask:0xf bank_mask:0xf bound_ctrl:1
	v_pk_fma_f32 v[220:221], v[146:147], v[212:213], v[220:221] op_sel_hi:[0,1,1] neg_lo:[1,0,0] neg_hi:[1,0,0]
	v_pk_fma_f32 v[222:223], v[146:147], v[214:215], v[222:223] op_sel_hi:[0,1,1] neg_lo:[1,0,0] neg_hi:[1,0,0]
	v_pk_fma_f32 v[138:139], v[138:139], v[216:217], v[220:221]
	v_pk_fma_f32 v[140:141], v[140:141], v[218:219], v[222:223]
	s_waitcnt lgkmcnt(6)
	v_pk_mul_f32 v[144:145], v[138:139], v[230:231]
	v_pk_fma_f32 v[144:145], v[140:141], v[232:233], v[144:145]
	v_add_f32 v146, v144, v145
	ds_read_b128 v[186:189], v5 offset:38400
	ds_read_b128 v[190:193], v5 offset:38656
	ds_read_b128 v[194:197], v5 offset:38912
	ds_read_b128 v[198:201], v5 offset:39168
	ds_read_b128 v[202:205], v5 offset:39424
	ds_read_b32 v206, v9 offset:38400
	v_add_f32_dpp v146, v146, v146 quad_perm:[1,0,3,2] row_mask:0xf bank_mask:0xf bound_ctrl:1
	v_pk_mul_f32 v[224:225], v[138:139], v[224:225]
	v_pk_fma_f32 v[224:225], v[140:141], v[226:227], v[224:225]
	v_add_f32_dpp v146, v146, v146 quad_perm:[2,3,0,1] row_mask:0xf bank_mask:0xf bound_ctrl:1
	v_add_f32 v154, v224, v225
	v_pk_mul_f32 v[242:243], v[242:243], v[250:251] op_sel_hi:[1,0]
	v_add_f32_dpp v146, v146, v146 row_half_mirror row_mask:0xf bank_mask:0xf bound_ctrl:1
	v_pk_mul_f32 v[244:245], v[244:245], v[250:251] op_sel_hi:[1,0]
	s_nop 0
	v_add_f32_dpp v146, v146, v146 row_mirror row_mask:0xf bank_mask:0xf bound_ctrl:1
	v_pk_fma_f32 v[242:243], v[146:147], v[234:235], v[242:243] op_sel_hi:[0,1,1] neg_lo:[1,0,0] neg_hi:[1,0,0]
	v_pk_fma_f32 v[244:245], v[146:147], v[236:237], v[244:245] op_sel_hi:[0,1,1] neg_lo:[1,0,0] neg_hi:[1,0,0]
	v_pk_fma_f32 v[138:139], v[138:139], v[238:239], v[242:243]
	v_pk_fma_f32 v[140:141], v[140:141], v[240:241], v[244:245]
	s_waitcnt lgkmcnt(6)
	v_pk_mul_f32 v[144:145], v[138:139], v[164:165]
	v_pk_fma_f32 v[144:145], v[140:141], v[166:167], v[144:145]
	v_add_f32 v146, v144, v145
	ds_read_b128 v[208:211], v5 offset:39936
	ds_read_b128 v[212:215], v5 offset:40192
	ds_read_b128 v[216:219], v5 offset:40448
	ds_read_b128 v[220:223], v5 offset:40704
	ds_read_b128 v[224:227], v5 offset:40960
	ds_read_b32 v228, v9 offset:39936
	v_add_f32_dpp v146, v146, v146 quad_perm:[1,0,3,2] row_mask:0xf bank_mask:0xf bound_ctrl:1
	v_pk_mul_f32 v[246:247], v[138:139], v[246:247]
	v_pk_fma_f32 v[246:247], v[140:141], v[248:249], v[246:247]
	v_add_f32_dpp v146, v146, v146 quad_perm:[2,3,0,1] row_mask:0xf bank_mask:0xf bound_ctrl:1
	v_add_f32 v155, v246, v247
	v_pk_mul_f32 v[176:177], v[176:177], v[184:185] op_sel_hi:[1,0]
	v_add_f32_dpp v146, v146, v146 row_half_mirror row_mask:0xf bank_mask:0xf bound_ctrl:1
	v_pk_mul_f32 v[178:179], v[178:179], v[184:185] op_sel_hi:[1,0]
	s_nop 0
	v_add_f32_dpp v146, v146, v146 row_mirror row_mask:0xf bank_mask:0xf bound_ctrl:1
	v_pk_fma_f32 v[176:177], v[146:147], v[168:169], v[176:177] op_sel_hi:[0,1,1] neg_lo:[1,0,0] neg_hi:[1,0,0]
	v_pk_fma_f32 v[178:179], v[146:147], v[170:171], v[178:179] op_sel_hi:[0,1,1] neg_lo:[1,0,0] neg_hi:[1,0,0]
	v_pk_fma_f32 v[138:139], v[138:139], v[172:173], v[176:177]
	v_pk_fma_f32 v[140:141], v[140:141], v[174:175], v[178:179]
	s_waitcnt lgkmcnt(6)
	v_pk_mul_f32 v[144:145], v[138:139], v[186:187]
	v_pk_fma_f32 v[144:145], v[140:141], v[188:189], v[144:145]
	v_add_f32 v146, v144, v145
	ds_read_b128 v[230:233], v5 offset:41472
	ds_read_b128 v[234:237], v5 offset:41728
	ds_read_b128 v[238:241], v5 offset:41984
	ds_read_b128 v[242:245], v5 offset:42240
	ds_read_b128 v[246:249], v5 offset:42496
	ds_read_b32 v250, v9 offset:41472
	v_add_f32_dpp v146, v146, v146 quad_perm:[1,0,3,2] row_mask:0xf bank_mask:0xf bound_ctrl:1
	v_pk_mul_f32 v[180:181], v[138:139], v[180:181]
	v_pk_fma_f32 v[180:181], v[140:141], v[182:183], v[180:181]
	v_add_f32_dpp v146, v146, v146 quad_perm:[2,3,0,1] row_mask:0xf bank_mask:0xf bound_ctrl:1
	v_add_f32 v156, v180, v181
	v_pk_mul_f32 v[198:199], v[198:199], v[206:207] op_sel_hi:[1,0]
	v_add_f32_dpp v146, v146, v146 row_half_mirror row_mask:0xf bank_mask:0xf bound_ctrl:1
	v_pk_mul_f32 v[200:201], v[200:201], v[206:207] op_sel_hi:[1,0]
	s_nop 0
	v_add_f32_dpp v146, v146, v146 row_mirror row_mask:0xf bank_mask:0xf bound_ctrl:1
	v_pk_fma_f32 v[198:199], v[146:147], v[190:191], v[198:199] op_sel_hi:[0,1,1] neg_lo:[1,0,0] neg_hi:[1,0,0]
	v_pk_fma_f32 v[200:201], v[146:147], v[192:193], v[200:201] op_sel_hi:[0,1,1] neg_lo:[1,0,0] neg_hi:[1,0,0]
	v_pk_fma_f32 v[138:139], v[138:139], v[194:195], v[198:199]
	v_pk_fma_f32 v[140:141], v[140:141], v[196:197], v[200:201]
	s_waitcnt lgkmcnt(6)
	v_pk_mul_f32 v[144:145], v[138:139], v[208:209]
	v_pk_fma_f32 v[144:145], v[140:141], v[210:211], v[144:145]
	v_add_f32 v146, v144, v145
	ds_read_b128 v[164:167], v5 offset:43008
	ds_read_b128 v[168:171], v5 offset:43264
	ds_read_b128 v[172:175], v5 offset:43520
	ds_read_b128 v[176:179], v5 offset:43776
	ds_read_b128 v[180:183], v5 offset:44032
	ds_read_b32 v184, v9 offset:43008
	v_add_f32_dpp v146, v146, v146 quad_perm:[1,0,3,2] row_mask:0xf bank_mask:0xf bound_ctrl:1
	v_pk_mul_f32 v[202:203], v[138:139], v[202:203]
	v_pk_fma_f32 v[202:203], v[140:141], v[204:205], v[202:203]
	v_add_f32_dpp v146, v146, v146 quad_perm:[2,3,0,1] row_mask:0xf bank_mask:0xf bound_ctrl:1
	v_add_f32 v157, v202, v203
	v_pk_mul_f32 v[220:221], v[220:221], v[228:229] op_sel_hi:[1,0]
	v_add_f32_dpp v146, v146, v146 row_half_mirror row_mask:0xf bank_mask:0xf bound_ctrl:1
	v_pk_mul_f32 v[222:223], v[222:223], v[228:229] op_sel_hi:[1,0]
	s_nop 0
	v_add_f32_dpp v146, v146, v146 row_mirror row_mask:0xf bank_mask:0xf bound_ctrl:1
	v_pk_fma_f32 v[220:221], v[146:147], v[212:213], v[220:221] op_sel_hi:[0,1,1] neg_lo:[1,0,0] neg_hi:[1,0,0]
	v_pk_fma_f32 v[222:223], v[146:147], v[214:215], v[222:223] op_sel_hi:[0,1,1] neg_lo:[1,0,0] neg_hi:[1,0,0]
	v_pk_fma_f32 v[138:139], v[138:139], v[216:217], v[220:221]
	v_pk_fma_f32 v[140:141], v[140:141], v[218:219], v[222:223]
	s_waitcnt lgkmcnt(6)
	v_pk_mul_f32 v[144:145], v[138:139], v[230:231]
	v_pk_fma_f32 v[144:145], v[140:141], v[232:233], v[144:145]
	v_add_f32 v146, v144, v145
	ds_read_b128 v[186:189], v5 offset:44544
	ds_read_b128 v[190:193], v5 offset:44800
	ds_read_b128 v[194:197], v5 offset:45056
	ds_read_b128 v[198:201], v5 offset:45312
	ds_read_b128 v[202:205], v5 offset:45568
	ds_read_b32 v206, v9 offset:44544
	v_add_f32_dpp v146, v146, v146 quad_perm:[1,0,3,2] row_mask:0xf bank_mask:0xf bound_ctrl:1
	v_pk_mul_f32 v[224:225], v[138:139], v[224:225]
	v_pk_fma_f32 v[224:225], v[140:141], v[226:227], v[224:225]
	v_add_f32_dpp v146, v146, v146 quad_perm:[2,3,0,1] row_mask:0xf bank_mask:0xf bound_ctrl:1
	v_add_f32 v158, v224, v225
	v_pk_mul_f32 v[242:243], v[242:243], v[250:251] op_sel_hi:[1,0]
	v_add_f32_dpp v146, v146, v146 row_half_mirror row_mask:0xf bank_mask:0xf bound_ctrl:1
	v_pk_mul_f32 v[244:245], v[244:245], v[250:251] op_sel_hi:[1,0]
	s_nop 0
	v_add_f32_dpp v146, v146, v146 row_mirror row_mask:0xf bank_mask:0xf bound_ctrl:1
	v_pk_fma_f32 v[242:243], v[146:147], v[234:235], v[242:243] op_sel_hi:[0,1,1] neg_lo:[1,0,0] neg_hi:[1,0,0]
	v_pk_fma_f32 v[244:245], v[146:147], v[236:237], v[244:245] op_sel_hi:[0,1,1] neg_lo:[1,0,0] neg_hi:[1,0,0]
	v_pk_fma_f32 v[138:139], v[138:139], v[238:239], v[242:243]
	v_pk_fma_f32 v[140:141], v[140:141], v[240:241], v[244:245]
	s_waitcnt lgkmcnt(6)
	v_pk_mul_f32 v[144:145], v[138:139], v[164:165]
	v_pk_fma_f32 v[144:145], v[140:141], v[166:167], v[144:145]
	v_add_f32 v146, v144, v145
	ds_read_b128 v[208:211], v5 offset:46080
	ds_read_b128 v[212:215], v5 offset:46336
	ds_read_b128 v[216:219], v5 offset:46592
	ds_read_b128 v[220:223], v5 offset:46848
	ds_read_b128 v[224:227], v5 offset:47104
	ds_read_b32 v228, v9 offset:46080
	v_add_f32_dpp v146, v146, v146 quad_perm:[1,0,3,2] row_mask:0xf bank_mask:0xf bound_ctrl:1
	v_pk_mul_f32 v[246:247], v[138:139], v[246:247]
	v_pk_fma_f32 v[246:247], v[140:141], v[248:249], v[246:247]
	v_add_f32_dpp v146, v146, v146 quad_perm:[2,3,0,1] row_mask:0xf bank_mask:0xf bound_ctrl:1
	v_add_f32 v159, v246, v247
	v_pk_mul_f32 v[176:177], v[176:177], v[184:185] op_sel_hi:[1,0]
	v_add_f32_dpp v146, v146, v146 row_half_mirror row_mask:0xf bank_mask:0xf bound_ctrl:1
	v_pk_mul_f32 v[178:179], v[178:179], v[184:185] op_sel_hi:[1,0]
	s_nop 0
	v_add_f32_dpp v146, v146, v146 row_mirror row_mask:0xf bank_mask:0xf bound_ctrl:1
	v_pk_fma_f32 v[176:177], v[146:147], v[168:169], v[176:177] op_sel_hi:[0,1,1] neg_lo:[1,0,0] neg_hi:[1,0,0]
	v_pk_fma_f32 v[178:179], v[146:147], v[170:171], v[178:179] op_sel_hi:[0,1,1] neg_lo:[1,0,0] neg_hi:[1,0,0]
	v_pk_fma_f32 v[138:139], v[138:139], v[172:173], v[176:177]
	v_pk_fma_f32 v[140:141], v[140:141], v[174:175], v[178:179]
	s_waitcnt lgkmcnt(6)
	v_pk_mul_f32 v[144:145], v[138:139], v[186:187]
	v_pk_fma_f32 v[144:145], v[140:141], v[188:189], v[144:145]
	v_add_f32 v146, v144, v145
	ds_read_b128 v[230:233], v5 offset:47616
	ds_read_b128 v[234:237], v5 offset:47872
	ds_read_b128 v[238:241], v5 offset:48128
	ds_read_b128 v[242:245], v5 offset:48384
	ds_read_b128 v[246:249], v5 offset:48640
	ds_read_b32 v250, v9 offset:47616
	v_add_f32_dpp v146, v146, v146 quad_perm:[1,0,3,2] row_mask:0xf bank_mask:0xf bound_ctrl:1
	v_pk_mul_f32 v[180:181], v[138:139], v[180:181]
	v_pk_fma_f32 v[180:181], v[140:141], v[182:183], v[180:181]
	v_add_f32_dpp v146, v146, v146 quad_perm:[2,3,0,1] row_mask:0xf bank_mask:0xf bound_ctrl:1
	v_add_f32 v160, v180, v181
	v_pk_mul_f32 v[198:199], v[198:199], v[206:207] op_sel_hi:[1,0]
	v_add_f32_dpp v146, v146, v146 row_half_mirror row_mask:0xf bank_mask:0xf bound_ctrl:1
	v_pk_mul_f32 v[200:201], v[200:201], v[206:207] op_sel_hi:[1,0]
	s_nop 0
	v_add_f32_dpp v146, v146, v146 row_mirror row_mask:0xf bank_mask:0xf bound_ctrl:1
	v_pk_fma_f32 v[198:199], v[146:147], v[190:191], v[198:199] op_sel_hi:[0,1,1] neg_lo:[1,0,0] neg_hi:[1,0,0]
	v_pk_fma_f32 v[200:201], v[146:147], v[192:193], v[200:201] op_sel_hi:[0,1,1] neg_lo:[1,0,0] neg_hi:[1,0,0]
	v_pk_fma_f32 v[138:139], v[138:139], v[194:195], v[198:199]
	v_pk_fma_f32 v[140:141], v[140:141], v[196:197], v[200:201]
	s_waitcnt lgkmcnt(6)
	v_pk_mul_f32 v[144:145], v[138:139], v[208:209]
	v_pk_fma_f32 v[144:145], v[140:141], v[210:211], v[144:145]
	v_add_f32 v146, v144, v145
	s_nop 1
	v_add_f32_dpp v146, v146, v146 quad_perm:[1,0,3,2] row_mask:0xf bank_mask:0xf bound_ctrl:1
	v_pk_mul_f32 v[202:203], v[138:139], v[202:203]
	v_pk_fma_f32 v[202:203], v[140:141], v[204:205], v[202:203]
	v_add_f32_dpp v146, v146, v146 quad_perm:[2,3,0,1] row_mask:0xf bank_mask:0xf bound_ctrl:1
	v_add_f32 v161, v202, v203
	v_pk_mul_f32 v[220:221], v[220:221], v[228:229] op_sel_hi:[1,0]
	v_add_f32_dpp v146, v146, v146 row_half_mirror row_mask:0xf bank_mask:0xf bound_ctrl:1
	v_pk_mul_f32 v[222:223], v[222:223], v[228:229] op_sel_hi:[1,0]
	s_nop 0
	v_add_f32_dpp v146, v146, v146 row_mirror row_mask:0xf bank_mask:0xf bound_ctrl:1
	v_pk_fma_f32 v[220:221], v[146:147], v[212:213], v[220:221] op_sel_hi:[0,1,1] neg_lo:[1,0,0] neg_hi:[1,0,0]
	v_pk_fma_f32 v[222:223], v[146:147], v[214:215], v[222:223] op_sel_hi:[0,1,1] neg_lo:[1,0,0] neg_hi:[1,0,0]
	v_pk_fma_f32 v[138:139], v[138:139], v[216:217], v[220:221]
	v_pk_fma_f32 v[140:141], v[140:141], v[218:219], v[222:223]
	s_waitcnt lgkmcnt(0)
	v_pk_mul_f32 v[144:145], v[138:139], v[230:231]
	v_pk_fma_f32 v[144:145], v[140:141], v[232:233], v[144:145]
	v_add_f32 v146, v144, v145
	s_nop 1
	v_add_f32_dpp v146, v146, v146 quad_perm:[1,0,3,2] row_mask:0xf bank_mask:0xf bound_ctrl:1
	v_pk_mul_f32 v[224:225], v[138:139], v[224:225]
	v_pk_fma_f32 v[224:225], v[140:141], v[226:227], v[224:225]
	v_add_f32_dpp v146, v146, v146 quad_perm:[2,3,0,1] row_mask:0xf bank_mask:0xf bound_ctrl:1
	v_add_f32 v162, v224, v225
	v_pk_mul_f32 v[242:243], v[242:243], v[250:251] op_sel_hi:[1,0]
	v_add_f32_dpp v146, v146, v146 row_half_mirror row_mask:0xf bank_mask:0xf bound_ctrl:1
	v_pk_mul_f32 v[244:245], v[244:245], v[250:251] op_sel_hi:[1,0]
	s_nop 0
	v_add_f32_dpp v146, v146, v146 row_mirror row_mask:0xf bank_mask:0xf bound_ctrl:1
	v_pk_fma_f32 v[242:243], v[146:147], v[234:235], v[242:243] op_sel_hi:[0,1,1] neg_lo:[1,0,0] neg_hi:[1,0,0]
	v_pk_fma_f32 v[244:245], v[146:147], v[236:237], v[244:245] op_sel_hi:[0,1,1] neg_lo:[1,0,0] neg_hi:[1,0,0]
	v_pk_fma_f32 v[138:139], v[138:139], v[238:239], v[242:243]
	v_pk_fma_f32 v[140:141], v[140:141], v[240:241], v[244:245]
	v_pk_mul_f32 v[246:247], v[138:139], v[246:247]
	v_pk_fma_f32 v[246:247], v[140:141], v[248:249], v[246:247]
	v_add_f32 v163, v246, v247
	s_nop 0
	v_add_f32_dpp v230, v148, v148 row_mirror row_mask:0xf bank_mask:0x3 bound_ctrl:1
	v_add_f32_dpp v230, v156, v156 row_mirror row_mask:0xf bank_mask:0xc bound_ctrl:1
	v_add_f32_dpp v231, v149, v149 row_mirror row_mask:0xf bank_mask:0x3 bound_ctrl:1
	v_add_f32_dpp v231, v157, v157 row_mirror row_mask:0xf bank_mask:0xc bound_ctrl:1
	v_add_f32_dpp v232, v150, v150 row_mirror row_mask:0xf bank_mask:0x3 bound_ctrl:1
	v_add_f32_dpp v232, v158, v158 row_mirror row_mask:0xf bank_mask:0xc bound_ctrl:1
	v_add_f32_dpp v233, v151, v151 row_mirror row_mask:0xf bank_mask:0x3 bound_ctrl:1
	v_add_f32_dpp v233, v159, v159 row_mirror row_mask:0xf bank_mask:0xc bound_ctrl:1
	v_add_f32_dpp v234, v152, v152 row_mirror row_mask:0xf bank_mask:0x3 bound_ctrl:1
	v_add_f32_dpp v234, v160, v160 row_mirror row_mask:0xf bank_mask:0xc bound_ctrl:1
	v_add_f32_dpp v235, v153, v153 row_mirror row_mask:0xf bank_mask:0x3 bound_ctrl:1
	v_add_f32_dpp v235, v161, v161 row_mirror row_mask:0xf bank_mask:0xc bound_ctrl:1
	v_add_f32_dpp v236, v154, v154 row_mirror row_mask:0xf bank_mask:0x3 bound_ctrl:1
	v_add_f32_dpp v236, v162, v162 row_mirror row_mask:0xf bank_mask:0xc bound_ctrl:1
	v_add_f32_dpp v237, v155, v155 row_mirror row_mask:0xf bank_mask:0x3 bound_ctrl:1
	v_add_f32_dpp v237, v163, v163 row_mirror row_mask:0xf bank_mask:0xc bound_ctrl:1
	v_add_f32_dpp v238, v230, v230 row_half_mirror row_mask:0xf bank_mask:0x5 bound_ctrl:1
	v_add_f32_dpp v238, v234, v234 row_half_mirror row_mask:0xf bank_mask:0xa bound_ctrl:1
	v_add_f32_dpp v239, v231, v231 row_half_mirror row_mask:0xf bank_mask:0x5 bound_ctrl:1
	v_add_f32_dpp v239, v235, v235 row_half_mirror row_mask:0xf bank_mask:0xa bound_ctrl:1
	v_add_f32_dpp v240, v232, v232 row_half_mirror row_mask:0xf bank_mask:0x5 bound_ctrl:1
	v_add_f32_dpp v240, v236, v236 row_half_mirror row_mask:0xf bank_mask:0xa bound_ctrl:1
	v_add_f32_dpp v241, v233, v233 row_half_mirror row_mask:0xf bank_mask:0x5 bound_ctrl:1
	v_add_f32_dpp v241, v237, v237 row_half_mirror row_mask:0xf bank_mask:0xa bound_ctrl:1
	s_mov_b32 vcc_lo, 0xcccccccc
	s_mov_b32 vcc_hi, 0xcccccccc
	v_cndmask_b32 v244, v240, v238, vcc
	v_cndmask_b32 v245, v241, v239, vcc
	v_cndmask_b32 v242, v238, v240, vcc
	v_cndmask_b32 v243, v239, v241, vcc
	v_add_f32_dpp v242, v244, v242 quad_perm:[2,3,0,1] row_mask:0xf bank_mask:0xf bound_ctrl:1
	v_add_f32_dpp v243, v245, v243 quad_perm:[2,3,0,1] row_mask:0xf bank_mask:0xf bound_ctrl:1
	s_mov_b32 vcc_lo, 0xaaaaaaaa
	s_mov_b32 vcc_hi, 0xaaaaaaaa
	v_cndmask_b32 v244, v243, v242, vcc
	v_cndmask_b32 v245, v242, v243, vcc
	s_nop 0
	v_add_f32_dpp v19, v244, v245 quad_perm:[1,0,3,2] row_mask:0xf bank_mask:0xf bound_ctrl:1

; #define SCAN_BAR() asm volatile("s_barrier" ::: "memory")
; __device__ __forceinline__ void scan_unit(const Ctx& C0, const float* scn, int T, int quarter, const float* S0, float* Sout, unsigned char* obase, int mode) {
;     ...
;             if (mode == 0) { *(float*)(obase + (size_t)(k * 32 + q) * UPITCH_B + rl * 4) = osel0; *(float*)(obase + (size_t)(k * 32 + 16 + q) * UPITCH_B + rl * 4) = osel1; }
;             SCAN_BAR();
	v_lshl_add_u64 v[14:15], v[6:7], 0, s[0:1]
	v_add_co_u32_e32 v16, vcc, 0xfc29000, v14
	s_mov_b32 s8, 0xfc7f000
	s_nop 0
	v_addc_co_u32_e32 v17, vcc, 0, v15, vcc
	global_store_dword v[16:17], v18, off offset:768
	v_add_co_u32_e32 v16, vcc, 0xfc54000, v14
	s_add_u32 s0, s0, 0xac000
	s_nop 0
	v_addc_co_u32_e32 v17, vcc, 0, v15, vcc
	global_store_dword v[16:17], v19, off offset:768
	s_barrier
	ds_read_b128 v[164:167], v10 offset:0
	ds_read_b128 v[168:171], v10 offset:256
	ds_read_b128 v[172:175], v10 offset:512
	ds_read_b128 v[176:179], v10 offset:768
	ds_read_b128 v[180:183], v10 offset:1024
	ds_read_b32 v184, v11 offset:0
	ds_read_b128 v[186:189], v10 offset:1536
	ds_read_b128 v[190:193], v10 offset:1792
	ds_read_b128 v[194:197], v10 offset:2048
	ds_read_b128 v[198:201], v10 offset:2304
	ds_read_b128 v[202:205], v10 offset:2560
	ds_read_b32 v206, v11 offset:1536
	s_waitcnt lgkmcnt(6)
	v_pk_mul_f32 v[144:145], v[138:139], v[164:165]
	v_pk_fma_f32 v[144:145], v[140:141], v[166:167], v[144:145]
	v_add_f32 v146, v144, v145
	ds_read_b128 v[208:211], v10 offset:3072
	ds_read_b128 v[212:215], v10 offset:3328
	ds_read_b128 v[216:219], v10 offset:3584
	ds_read_b128 v[220:223], v10 offset:3840
	ds_read_b128 v[224:227], v10 offset:4096
	ds_read_b32 v228, v11 offset:3072
	v_add_f32_dpp v146, v146, v146 quad_perm:[1,0,3,2] row_mask:0xf bank_mask:0xf bound_ctrl:1
	s_nop 0
	s_nop 0
	v_add_f32_dpp v146, v146, v146 quad_perm:[2,3,0,1] row_mask:0xf bank_mask:0xf bound_ctrl:1
	s_nop 0
	v_pk_mul_f32 v[176:177], v[176:177], v[184:185] op_sel_hi:[1,0]
	v_add_f32_dpp v146, v146, v146 row_half_mirror row_mask:0xf bank_mask:0xf bound_ctrl:1
	v_pk_mul_f32 v[178:179], v[178:179], v[184:185] op_sel_hi:[1,0]
	s_nop 0
	v_add_f32_dpp v146, v146, v146 row_mirror row_mask:0xf bank_mask:0xf bound_ctrl:1
	v_pk_fma_f32 v[176:177], v[146:147], v[168:169], v[176:177] op_sel_hi:[0,1,1] neg_lo:[1,0,0] neg_hi:[1,0,0]
	v_pk_fma_f32 v[178:179], v[146:147], v[170:171], v[178:179] op_sel_hi:[0,1,1] neg_lo:[1,0,0] neg_hi:[1,0,0]
	v_pk_fma_f32 v[138:139], v[138:139], v[172:173], v[176:177]
	v_pk_fma_f32 v[140:141], v[140:141], v[174:175], v[178:179]
	s_waitcnt lgkmcnt(6)
	v_pk_mul_f32 v[144:145], v[138:139], v[186:187]
	v_pk_fma_f32 v[144:145], v[140:141], v[188:189], v[144:145]
	v_add_f32 v146, v144, v145
	ds_read_b128 v[230:233], v10 offset:4608
	ds_read_b128 v[234:237], v10 offset:4864
	ds_read_b128 v[238:241], v10 offset:5120
	ds_read_b128 v[242:245], v10 offset:5376
	ds_read_b128 v[246:249], v10 offset:5632
	ds_read_b32 v250, v11 offset:4608
	v_add_f32_dpp v146, v146, v146 quad_perm:[1,0,3,2] row_mask:0xf bank_mask:0xf bound_ctrl:1
	v_pk_mul_f32 v[180:181], v[138:139], v[180:181]
	v_pk_fma_f32 v[180:181], v[140:141], v[182:183], v[180:181]
	v_add_f32_dpp v146, v146, v146 quad_perm:[2,3,0,1] row_mask:0xf bank_mask:0xf bound_ctrl:1
	v_add_f32 v148, v180, v181
	v_pk_mul_f32 v[198:199], v[198:199], v[206:207] op_sel_hi:[1,0]
	v_add_f32_dpp v146, v146, v146 row_half_mirror row_mask:0xf bank_mask:0xf bound_ctrl:1
	v_pk_mul_f32 v[200:201], v[200:201], v[206:207] op_sel_hi:[1,0]
	s_nop 0
	v_add_f32_dpp v146, v146, v146 row_mirror row_mask:0xf bank_mask:0xf bound_ctrl:1
	v_pk_fma_f32 v[198:199], v[146:147], v[190:191], v[198:199] op_sel_hi:[0,1,1] neg_lo:[1,0,0] neg_hi:[1,0,0]
	v_pk_fma_f32 v[200:201], v[146:147], v[192:193], v[200:201] op_sel_hi:[0,1,1] neg_lo:[1,0,0] neg_hi:[1,0,0]
	v_pk_fma_f32 v[138:139], v[138:139], v[194:195], v[198:199]
	v_pk_fma_f32 v[140:141], v[140:141], v[196:197], v[200:201]
	s_waitcnt lgkmcnt(6)
	v_pk_mul_f32 v[144:145], v[138:139], v[208:209]
	v_pk_fma_f32 v[144:145], v[140:141], v[210:211], v[144:145]
	v_add_f32 v146, v144, v145
	ds_read_b128 v[164:167], v10 offset:6144
	ds_read_b128 v[168:171], v10 offset:6400
	ds_read_b128 v[172:175], v10 offset:6656
	ds_read_b128 v[176:179], v10 offset:6912
	ds_read_b128 v[180:183], v10 offset:7168
	ds_read_b32 v184, v11 offset:6144
	v_add_f32_dpp v146, v146, v146 quad_perm:[1,0,3,2] row_mask:0xf bank_mask:0xf bound_ctrl:1
	v_pk_mul_f32 v[202:203], v[138:139], v[202:203]
	v_pk_fma_f32 v[202:203], v[140:141], v[204:205], v[202:203]
	v_add_f32_dpp v146, v146, v146 quad_perm:[2,3,0,1] row_mask:0xf bank_mask:0xf bound_ctrl:1
	v_add_f32 v149, v202, v203
	v_pk_mul_f32 v[220:221], v[220:221], v[228:229] op_sel_hi:[1,0]
	v_add_f32_dpp v146, v146, v146 row_half_mirror row_mask:0xf bank_mask:0xf bound_ctrl:1
	v_pk_mul_f32 v[222:223], v[222:223], v[228:229] op_sel_hi:[1,0]
	s_nop 0
	v_add_f32_dpp v146, v146, v146 row_mirror row_mask:0xf bank_mask:0xf bound_ctrl:1
	v_pk_fma_f32 v[220:221], v[146:147], v[212:213], v[220:221] op_sel_hi:[0,1,1] neg_lo:[1,0,0] neg_hi:[1,0,0]
	v_pk_fma_f32 v[222:223], v[146:147], v[214:215], v[222:223] op_sel_hi:[0,1,1] neg_lo:[1,0,0] neg_hi:[1,0,0]
	v_pk_fma_f32 v[138:139], v[138:139], v[216:217], v[220:221]
	v_pk_fma_f32 v[140:141], v[140:141], v[218:219], v[222:223]
	s_waitcnt lgkmcnt(6)
	v_pk_mul_f32 v[144:145], v[138:139], v[230:231]
	v_pk_fma_f32 v[144:145], v[140:141], v[232:233], v[144:145]
	v_add_f32 v146, v144, v145
	ds_read_b128 v[186:189], v10 offset:7680
	ds_read_b128 v[190:193], v10 offset:7936
	ds_read_b128 v[194:197], v10 offset:8192
	ds_read_b128 v[198:201], v10 offset:8448
	ds_read_b128 v[202:205], v10 offset:8704
	ds_read_b32 v206, v11 offset:7680
	v_add_f32_dpp v146, v146, v146 quad_perm:[1,0,3,2] row_mask:0xf bank_mask:0xf bound_ctrl:1
	v_pk_mul_f32 v[224:225], v[138:139], v[224:225]
	v_pk_fma_f32 v[224:225], v[140:141], v[226:227], v[224:225]
	v_add_f32_dpp v146, v146, v146 quad_perm:[2,3,0,1] row_mask:0xf bank_mask:0xf bound_ctrl:1
	v_add_f32 v150, v224, v225
	v_pk_mul_f32 v[242:243], v[242:243], v[250:251] op_sel_hi:[1,0]
	v_add_f32_dpp v146, v146, v146 row_half_mirror row_mask:0xf bank_mask:0xf bound_ctrl:1
	v_pk_mul_f32 v[244:245], v[244:245], v[250:251] op_sel_hi:[1,0]
	s_nop 0
	v_add_f32_dpp v146, v146, v146 row_mirror row_mask:0xf bank_mask:0xf bound_ctrl:1
	v_pk_fma_f32 v[242:243], v[146:147], v[234:235], v[242:243] op_sel_hi:[0,1,1] neg_lo:[1,0,0] neg_hi:[1,0,0]
	v_pk_fma_f32 v[244:245], v[146:147], v[236:237], v[244:245] op_sel_hi:[0,1,1] neg_lo:[1,0,0] neg_hi:[1,0,0]
	v_pk_fma_f32 v[138:139], v[138:139], v[238:239], v[242:243]
	v_pk_fma_f32 v[140:141], v[140:141], v[240:241], v[244:245]
	s_waitcnt lgkmcnt(6)
	v_pk_mul_f32 v[144:145], v[138:139], v[164:165]
	v_pk_fma_f32 v[144:145], v[140:141], v[166:167], v[144:145]
	v_add_f32 v146, v144, v145
	ds_read_b128 v[208:211], v10 offset:9216
	ds_read_b128 v[212:215], v10 offset:9472
	ds_read_b128 v[216:219], v10 offset:9728
	ds_read_b128 v[220:223], v10 offset:9984
	ds_read_b128 v[224:227], v10 offset:10240
	ds_read_b32 v228, v11 offset:9216
	v_add_f32_dpp v146, v146, v146 quad_perm:[1,0,3,2] row_mask:0xf bank_mask:0xf bound_ctrl:1
	v_pk_mul_f32 v[246:247], v[138:139], v[246:247]
	v_pk_fma_f32 v[246:247], v[140:141], v[248:249], v[246:247]
	v_add_f32_dpp v146, v146, v146 quad_perm:[2,3,0,1] row_mask:0xf bank_mask:0xf bound_ctrl:1
	v_add_f32 v151, v246, v247
	v_pk_mul_f32 v[176:177], v[176:177], v[184:185] op_sel_hi:[1,0]
	v_add_f32_dpp v146, v146, v146 row_half_mirror row_mask:0xf bank_mask:0xf bound_ctrl:1
	v_pk_mul_f32 v[178:179], v[178:179], v[184:185] op_sel_hi:[1,0]
	s_nop 0
	v_add_f32_dpp v146, v146, v146 row_mirror row_mask:0xf bank_mask:0xf bound_ctrl:1
	v_pk_fma_f32 v[176:177], v[146:147], v[168:169], v[176:177] op_sel_hi:[0,1,1] neg_lo:[1,0,0] neg_hi:[1,0,0]
	v_pk_fma_f32 v[178:179], v[146:147], v[170:171], v[178:179] op_sel_hi:[0,1,1] neg_lo:[1,0,0] neg_hi:[1,0,0]
	v_pk_fma_f32 v[138:139], v[138:139], v[172:173], v[176:177]
	v_pk_fma_f32 v[140:141], v[140:141], v[174:175], v[178:179]
	s_waitcnt lgkmcnt(6)
	v_pk_mul_f32 v[144:145], v[138:139], v[186:187]
	v_pk_fma_f32 v[144:145], v[140:141], v[188:189], v[144:145]
	v_add_f32 v146, v144, v145
	ds_read_b128 v[230:233], v10 offset:10752
	ds_read_b128 v[234:237], v10 offset:11008
	ds_read_b128 v[238:241], v10 offset:11264
	ds_read_b128 v[242:245], v10 offset:11520
	ds_read_b128 v[246:249], v10 offset:11776
	ds_read_b32 v250, v11 offset:10752
	v_add_f32_dpp v146, v146, v146 quad_perm:[1,0,3,2] row_mask:0xf bank_mask:0xf bound_ctrl:1
	v_pk_mul_f32 v[180:181], v[138:139], v[180:181]
	v_pk_fma_f32 v[180:181], v[140:141], v[182:183], v[180:181]
	v_add_f32_dpp v146, v146, v146 quad_perm:[2,3,0,1] row_mask:0xf bank_mask:0xf bound_ctrl:1
	v_add_f32 v152, v180, v181
	v_pk_mul_f32 v[198:199], v[198:199], v[206:207] op_sel_hi:[1,0]
	v_add_f32_dpp v146, v146, v146 row_half_mirror row_mask:0xf bank_mask:0xf bound_ctrl:1
	v_pk_mul_f32 v[200:201], v[200:201], v[206:207] op_sel_hi:[1,0]
	s_nop 0
	v_add_f32_dpp v146, v146, v146 row_mirror row_mask:0xf bank_mask:0xf bound_ctrl:1
	v_pk_fma_f32 v[198:199], v[146:147], v[190:191], v[198:199] op_sel_hi:[0,1,1] neg_lo:[1,0,0] neg_hi:[1,0,0]
	v_pk_fma_f32 v[200:201], v[146:147], v[192:193], v[200:201] op_sel_hi:[0,1,1] neg_lo:[1,0,0] neg_hi:[1,0,0]
	v_pk_fma_f32 v[138:139], v[138:139], v[194:195], v[198:199]
	v_pk_fma_f32 v[140:141], v[140:141], v[196:197], v[200:201]
	s_waitcnt lgkmcnt(6)
	v_pk_mul_f32 v[144:145], v[138:139], v[208:209]
	v_pk_fma_f32 v[144:145], v[140:141], v[210:211], v[144:145]
	v_add_f32 v146, v144, v145
	ds_read_b128 v[164:167], v10 offset:12288
	ds_read_b128 v[168:171], v10 offset:12544
	ds_read_b128 v[172:175], v10 offset:12800
	ds_read_b128 v[176:179], v10 offset:13056
	ds_read_b128 v[180:183], v10 offset:13312
	ds_read_b32 v184, v11 offset:12288
	v_add_f32_dpp v146, v146, v146 quad_perm:[1,0,3,2] row_mask:0xf bank_mask:0xf bound_ctrl:1
	v_pk_mul_f32 v[202:203], v[138:139], v[202:203]
	v_pk_fma_f32 v[202:203], v[140:141], v[204:205], v[202:203]
	v_add_f32_dpp v146, v146, v146 quad_perm:[2,3,0,1] row_mask:0xf bank_mask:0xf bound_ctrl:1
	v_add_f32 v153, v202, v203
	v_pk_mul_f32 v[220:221], v[220:221], v[228:229] op_sel_hi:[1,0]
	v_add_f32_dpp v146, v146, v146 row_half_mirror row_mask:0xf bank_mask:0xf bound_ctrl:1
	v_pk_mul_f32 v[222:223], v[222:223], v[228:229] op_sel_hi:[1,0]
	s_nop 0
	v_add_f32_dpp v146, v146, v146 row_mirror row_mask:0xf bank_mask:0xf bound_ctrl:1
	v_pk_fma_f32 v[220:221], v[146:147], v[212:213], v[220:221] op_sel_hi:[0,1,1] neg_lo:[1,0,0] neg_hi:[1,0,0]
	v_pk_fma_f32 v[222:223], v[146:147], v[214:215], v[222:223] op_sel_hi:[0,1,1] neg_lo:[1,0,0] neg_hi:[1,0,0]
	v_pk_fma_f32 v[138:139], v[138:139], v[216:217], v[220:221]
	v_pk_fma_f32 v[140:141], v[140:141], v[218:219], v[222:223]
	s_waitcnt lgkmcnt(6)
	v_pk_mul_f32 v[144:145], v[138:139], v[230:231]
	v_pk_fma_f32 v[144:145], v[140:141], v[232:233], v[144:145]
	v_add_f32 v146, v144, v145
	ds_read_b128 v[186:189], v10 offset:13824
	ds_read_b128 v[190:193], v10 offset:14080
	ds_read_b128 v[194:197], v10 offset:14336
	ds_read_b128 v[198:201], v10 offset:14592
	ds_read_b128 v[202:205], v10 offset:14848
	ds_read_b32 v206, v11 offset:13824
	v_add_f32_dpp v146, v146, v146 quad_perm:[1,0,3,2] row_mask:0xf bank_mask:0xf bound_ctrl:1
	v_pk_mul_f32 v[224:225], v[138:139], v[224:225]
	v_pk_fma_f32 v[224:225], v[140:141], v[226:227], v[224:225]
	v_add_f32_dpp v146, v146, v146 quad_perm:[2,3,0,1] row_mask:0xf bank_mask:0xf bound_ctrl:1
	v_add_f32 v154, v224, v225
	v_pk_mul_f32 v[242:243], v[242:243], v[250:251] op_sel_hi:[1,0]
	v_add_f32_dpp v146, v146, v146 row_half_mirror row_mask:0xf bank_mask:0xf bound_ctrl:1
	v_pk_mul_f32 v[244:245], v[244:245], v[250:251] op_sel_hi:[1,0]
	s_nop 0
	v_add_f32_dpp v146, v146, v146 row_mirror row_mask:0xf bank_mask:0xf bound_ctrl:1
	v_pk_fma_f32 v[242:243], v[146:147], v[234:235], v[242:243] op_sel_hi:[0,1,1] neg_lo:[1,0,0] neg_hi:[1,0,0]
	v_pk_fma_f32 v[244:245], v[146:147], v[236:237], v[244:245] op_sel_hi:[0,1,1] neg_lo:[1,0,0] neg_hi:[1,0,0]
	v_pk_fma_f32 v[138:139], v[138:139], v[238:239], v[242:243]
	v_pk_fma_f32 v[140:141], v[140:141], v[240:241], v[244:245]
	s_waitcnt lgkmcnt(6)
	v_pk_mul_f32 v[144:145], v[138:139], v[164:165]
	v_pk_fma_f32 v[144:145], v[140:141], v[166:167], v[144:145]
	v_add_f32 v146, v144, v145
	ds_read_b128 v[208:211], v10 offset:15360
	ds_read_b128 v[212:215], v10 offset:15616
	ds_read_b128 v[216:219], v10 offset:15872
	ds_read_b128 v[220:223], v10 offset:16128
	ds_read_b128 v[224:227], v10 offset:16384
	ds_read_b32 v228, v11 offset:15360
	v_add_f32_dpp v146, v146, v146 quad_perm:[1,0,3,2] row_mask:0xf bank_mask:0xf bound_ctrl:1
	v_pk_mul_f32 v[246:247], v[138:139], v[246:247]
	v_pk_fma_f32 v[246:247], v[140:141], v[248:249], v[246:247]
	v_add_f32_dpp v146, v146, v146 quad_perm:[2,3,0,1] row_mask:0xf bank_mask:0xf bound_ctrl:1
	v_add_f32 v155, v246, v247
	v_pk_mul_f32 v[176:177], v[176:177], v[184:185] op_sel_hi:[1,0]
	v_add_f32_dpp v146, v146, v146 row_half_mirror row_mask:0xf bank_mask:0xf bound_ctrl:1
	v_pk_mul_f32 v[178:179], v[178:179], v[184:185] op_sel_hi:[1,0]
	s_nop 0
	v_add_f32_dpp v146, v146, v146 row_mirror row_mask:0xf bank_mask:0xf bound_ctrl:1
	v_pk_fma_f32 v[176:177], v[146:147], v[168:169], v[176:177] op_sel_hi:[0,1,1] neg_lo:[1,0,0] neg_hi:[1,0,0]
	v_pk_fma_f32 v[178:179], v[146:147], v[170:171], v[178:179] op_sel_hi:[0,1,1] neg_lo:[1,0,0] neg_hi:[1,0,0]
	v_pk_fma_f32 v[138:139], v[138:139], v[172:173], v[176:177]
	v_pk_fma_f32 v[140:141], v[140:141], v[174:175], v[178:179]
	s_waitcnt lgkmcnt(6)
	v_pk_mul_f32 v[144:145], v[138:139], v[186:187]
	v_pk_fma_f32 v[144:145], v[140:141], v[188:189], v[144:145]
	v_add_f32 v146, v144, v145
	ds_read_b128 v[230:233], v10 offset:16896
	ds_read_b128 v[234:237], v10 offset:17152
	ds_read_b128 v[238:241], v10 offset:17408
	ds_read_b128 v[242:245], v10 offset:17664
	ds_read_b128 v[246:249], v10 offset:17920
	ds_read_b32 v250, v11 offset:16896
	v_add_f32_dpp v146, v146, v146 quad_perm:[1,0,3,2] row_mask:0xf bank_mask:0xf bound_ctrl:1
	v_pk_mul_f32 v[180:181], v[138:139], v[180:181]
	v_pk_fma_f32 v[180:181], v[140:141], v[182:183], v[180:181]
	v_add_f32_dpp v146, v146, v146 quad_perm:[2,3,0,1] row_mask:0xf bank_mask:0xf bound_ctrl:1
	v_add_f32 v156, v180, v181
	v_pk_mul_f32 v[198:199], v[198:199], v[206:207] op_sel_hi:[1,0]
	v_add_f32_dpp v146, v146, v146 row_half_mirror row_mask:0xf bank_mask:0xf bound_ctrl:1
	v_pk_mul_f32 v[200:201], v[200:201], v[206:207] op_sel_hi:[1,0]
	s_nop 0
	v_add_f32_dpp v146, v146, v146 row_mirror row_mask:0xf bank_mask:0xf bound_ctrl:1
	v_pk_fma_f32 v[198:199], v[146:147], v[190:191], v[198:199] op_sel_hi:[0,1,1] neg_lo:[1,0,0] neg_hi:[1,0,0]
	v_pk_fma_f32 v[200:201], v[146:147], v[192:193], v[200:201] op_sel_hi:[0,1,1] neg_lo:[1,0,0] neg_hi:[1,0,0]
	v_pk_fma_f32 v[138:139], v[138:139], v[194:195], v[198:199]
	v_pk_fma_f32 v[140:141], v[140:141], v[196:197], v[200:201]
	s_waitcnt lgkmcnt(6)
	v_pk_mul_f32 v[144:145], v[138:139], v[208:209]
	v_pk_fma_f32 v[144:145], v[140:141], v[210:211], v[144:145]
	v_add_f32 v146, v144, v145
	ds_read_b128 v[164:167], v10 offset:18432
	ds_read_b128 v[168:171], v10 offset:18688
	ds_read_b128 v[172:175], v10 offset:18944
	ds_read_b128 v[176:179], v10 offset:19200
	ds_read_b128 v[180:183], v10 offset:19456
	ds_read_b32 v184, v11 offset:18432
	v_add_f32_dpp v146, v146, v146 quad_perm:[1,0,3,2] row_mask:0xf bank_mask:0xf bound_ctrl:1
	v_pk_mul_f32 v[202:203], v[138:139], v[202:203]
	v_pk_fma_f32 v[202:203], v[140:141], v[204:205], v[202:203]
	v_add_f32_dpp v146, v146, v146 quad_perm:[2,3,0,1] row_mask:0xf bank_mask:0xf bound_ctrl:1
	v_add_f32 v157, v202, v203
	v_pk_mul_f32 v[220:221], v[220:221], v[228:229] op_sel_hi:[1,0]
	v_add_f32_dpp v146, v146, v146 row_half_mirror row_mask:0xf bank_mask:0xf bound_ctrl:1
	v_pk_mul_f32 v[222:223], v[222:223], v[228:229] op_sel_hi:[1,0]
	s_nop 0
	v_add_f32_dpp v146, v146, v146 row_mirror row_mask:0xf bank_mask:0xf bound_ctrl:1
	v_pk_fma_f32 v[220:221], v[146:147], v[212:213], v[220:221] op_sel_hi:[0,1,1] neg_lo:[1,0,0] neg_hi:[1,0,0]
	v_pk_fma_f32 v[222:223], v[146:147], v[214:215], v[222:223] op_sel_hi:[0,1,1] neg_lo:[1,0,0] neg_hi:[1,0,0]
	v_pk_fma_f32 v[138:139], v[138:139], v[216:217], v[220:221]
	v_pk_fma_f32 v[140:141], v[140:141], v[218:219], v[222:223]
	s_waitcnt lgkmcnt(6)
	v_pk_mul_f32 v[144:145], v[138:139], v[230:231]
	v_pk_fma_f32 v[144:145], v[140:141], v[232:233], v[144:145]
	v_add_f32 v146, v144, v145
	ds_read_b128 v[186:189], v10 offset:19968
	ds_read_b128 v[190:193], v10 offset:20224
	ds_read_b128 v[194:197], v10 offset:20480
	ds_read_b128 v[198:201], v10 offset:20736
	ds_read_b128 v[202:205], v10 offset:20992
	ds_read_b32 v206, v11 offset:19968
	v_add_f32_dpp v146, v146, v146 quad_perm:[1,0,3,2] row_mask:0xf bank_mask:0xf bound_ctrl:1
	v_pk_mul_f32 v[224:225], v[138:139], v[224:225]
	v_pk_fma_f32 v[224:225], v[140:141], v[226:227], v[224:225]
	v_add_f32_dpp v146, v146, v146 quad_perm:[2,3,0,1] row_mask:0xf bank_mask:0xf bound_ctrl:1
	v_add_f32 v158, v224, v225
	v_pk_mul_f32 v[242:243], v[242:243], v[250:251] op_sel_hi:[1,0]
	v_add_f32_dpp v146, v146, v146 row_half_mirror row_mask:0xf bank_mask:0xf bound_ctrl:1
	v_pk_mul_f32 v[244:245], v[244:245], v[250:251] op_sel_hi:[1,0]
	s_nop 0
	v_add_f32_dpp v146, v146, v146 row_mirror row_mask:0xf bank_mask:0xf bound_ctrl:1
	v_pk_fma_f32 v[242:243], v[146:147], v[234:235], v[242:243] op_sel_hi:[0,1,1] neg_lo:[1,0,0] neg_hi:[1,0,0]
	v_pk_fma_f32 v[244:245], v[146:147], v[236:237], v[244:245] op_sel_hi:[0,1,1] neg_lo:[1,0,0] neg_hi:[1,0,0]
	v_pk_fma_f32 v[138:139], v[138:139], v[238:239], v[242:243]
	v_pk_fma_f32 v[140:141], v[140:141], v[240:241], v[244:245]
	s_waitcnt lgkmcnt(6)
	v_pk_mul_f32 v[144:145], v[138:139], v[164:165]
	v_pk_fma_f32 v[144:145], v[140:141], v[166:167], v[144:145]
	v_add_f32 v146, v144, v145
	ds_read_b128 v[208:211], v10 offset:21504
	ds_read_b128 v[212:215], v10 offset:21760
	ds_read_b128 v[216:219], v10 offset:22016
	ds_read_b128 v[220:223], v10 offset:22272
	ds_read_b128 v[224:227], v10 offset:22528
	ds_read_b32 v228, v11 offset:21504
	v_add_f32_dpp v146, v146, v146 quad_perm:[1,0,3,2] row_mask:0xf bank_mask:0xf bound_ctrl:1
	v_pk_mul_f32 v[246:247], v[138:139], v[246:247]
	v_pk_fma_f32 v[246:247], v[140:141], v[248:249], v[246:247]
	v_add_f32_dpp v146, v146, v146 quad_perm:[2,3,0,1] row_mask:0xf bank_mask:0xf bound_ctrl:1
	v_add_f32 v159, v246, v247
	v_pk_mul_f32 v[176:177], v[176:177], v[184:185] op_sel_hi:[1,0]
	v_add_f32_dpp v146, v146, v146 row_half_mirror row_mask:0xf bank_mask:0xf bound_ctrl:1
	v_pk_mul_f32 v[178:179], v[178:179], v[184:185] op_sel_hi:[1,0]
	s_nop 0
	v_add_f32_dpp v146, v146, v146 row_mirror row_mask:0xf bank_mask:0xf bound_ctrl:1
	v_pk_fma_f32 v[176:177], v[146:147], v[168:169], v[176:177] op_sel_hi:[0,1,1] neg_lo:[1,0,0] neg_hi:[1,0,0]
	v_pk_fma_f32 v[178:179], v[146:147], v[170:171], v[178:179] op_sel_hi:[0,1,1] neg_lo:[1,0,0] neg_hi:[1,0,0]
	v_pk_fma_f32 v[138:139], v[138:139], v[172:173], v[176:177]
	v_pk_fma_f32 v[140:141], v[140:141], v[174:175], v[178:179]
	s_waitcnt lgkmcnt(6)
	v_pk_mul_f32 v[144:145], v[138:139], v[186:187]
	v_pk_fma_f32 v[144:145], v[140:141], v[188:189], v[144:145]
	v_add_f32 v146, v144, v145
	ds_read_b128 v[230:233], v10 offset:23040
	ds_read_b128 v[234:237], v10 offset:23296
	ds_read_b128 v[238:241], v10 offset:23552
	ds_read_b128 v[242:245], v10 offset:23808
	ds_read_b128 v[246:249], v10 offset:24064
	ds_read_b32 v250, v11 offset:23040
	v_add_f32_dpp v146, v146, v146 quad_perm:[1,0,3,2] row_mask:0xf bank_mask:0xf bound_ctrl:1
	v_pk_mul_f32 v[180:181], v[138:139], v[180:181]
	v_pk_fma_f32 v[180:181], v[140:141], v[182:183], v[180:181]
	v_add_f32_dpp v146, v146, v146 quad_perm:[2,3,0,1] row_mask:0xf bank_mask:0xf bound_ctrl:1
	v_add_f32 v160, v180, v181
	v_pk_mul_f32 v[198:199], v[198:199], v[206:207] op_sel_hi:[1,0]
	v_add_f32_dpp v146, v146, v146 row_half_mirror row_mask:0xf bank_mask:0xf bound_ctrl:1
	v_pk_mul_f32 v[200:201], v[200:201], v[206:207] op_sel_hi:[1,0]
	s_nop 0
	v_add_f32_dpp v146, v146, v146 row_mirror row_mask:0xf bank_mask:0xf bound_ctrl:1
	v_pk_fma_f32 v[198:199], v[146:147], v[190:191], v[198:199] op_sel_hi:[0,1,1] neg_lo:[1,0,0] neg_hi:[1,0,0]
	v_pk_fma_f32 v[200:201], v[146:147], v[192:193], v[200:201] op_sel_hi:[0,1,1] neg_lo:[1,0,0] neg_hi:[1,0,0]
	v_pk_fma_f32 v[138:139], v[138:139], v[194:195], v[198:199]
	v_pk_fma_f32 v[140:141], v[140:141], v[196:197], v[200:201]
	s_waitcnt lgkmcnt(6)
	v_pk_mul_f32 v[144:145], v[138:139], v[208:209]
	v_pk_fma_f32 v[144:145], v[140:141], v[210:211], v[144:145]
	v_add_f32 v146, v144, v145
	ds_read_b128 v[164:167], v10 offset:24576
	ds_read_b128 v[168:171], v10 offset:24832
	ds_read_b128 v[172:175], v10 offset:25088
	ds_read_b128 v[176:179], v10 offset:25344
	ds_read_b128 v[180:183], v10 offset:25600
	ds_read_b32 v184, v11 offset:24576
	v_add_f32_dpp v146, v146, v146 quad_perm:[1,0,3,2] row_mask:0xf bank_mask:0xf bound_ctrl:1
	v_pk_mul_f32 v[202:203], v[138:139], v[202:203]
	v_pk_fma_f32 v[202:203], v[140:141], v[204:205], v[202:203]
	v_add_f32_dpp v146, v146, v146 quad_perm:[2,3,0,1] row_mask:0xf bank_mask:0xf bound_ctrl:1
	v_add_f32 v161, v202, v203
	v_pk_mul_f32 v[220:221], v[220:221], v[228:229] op_sel_hi:[1,0]
	v_add_f32_dpp v146, v146, v146 row_half_mirror row_mask:0xf bank_mask:0xf bound_ctrl:1
	v_pk_mul_f32 v[222:223], v[222:223], v[228:229] op_sel_hi:[1,0]
	s_nop 0
	v_add_f32_dpp v146, v146, v146 row_mirror row_mask:0xf bank_mask:0xf bound_ctrl:1
	v_pk_fma_f32 v[220:221], v[146:147], v[212:213], v[220:221] op_sel_hi:[0,1,1] neg_lo:[1,0,0] neg_hi:[1,0,0]
	v_pk_fma_f32 v[222:223], v[146:147], v[214:215], v[222:223] op_sel_hi:[0,1,1] neg_lo:[1,0,0] neg_hi:[1,0,0]
	v_pk_fma_f32 v[138:139], v[138:139], v[216:217], v[220:221]
	v_pk_fma_f32 v[140:141], v[140:141], v[218:219], v[222:223]
	s_waitcnt lgkmcnt(6)
	v_pk_mul_f32 v[144:145], v[138:139], v[230:231]
	v_pk_fma_f32 v[144:145], v[140:141], v[232:233], v[144:145]
	v_add_f32 v146, v144, v145
	ds_read_b128 v[186:189], v10 offset:26112
	ds_read_b128 v[190:193], v10 offset:26368
	ds_read_b128 v[194:197], v10 offset:26624
	ds_read_b128 v[198:201], v10 offset:26880
	ds_read_b128 v[202:205], v10 offset:27136
	ds_read_b32 v206, v11 offset:26112
	v_add_f32_dpp v146, v146, v146 quad_perm:[1,0,3,2] row_mask:0xf bank_mask:0xf bound_ctrl:1
	v_pk_mul_f32 v[224:225], v[138:139], v[224:225]
	v_pk_fma_f32 v[224:225], v[140:141], v[226:227], v[224:225]
	v_add_f32_dpp v146, v146, v146 quad_perm:[2,3,0,1] row_mask:0xf bank_mask:0xf bound_ctrl:1
	v_add_f32 v162, v224, v225
	v_pk_mul_f32 v[242:243], v[242:243], v[250:251] op_sel_hi:[1,0]
	v_add_f32_dpp v146, v146, v146 row_half_mirror row_mask:0xf bank_mask:0xf bound_ctrl:1
	v_pk_mul_f32 v[244:245], v[244:245], v[250:251] op_sel_hi:[1,0]
	s_nop 0
	v_add_f32_dpp v146, v146, v146 row_mirror row_mask:0xf bank_mask:0xf bound_ctrl:1
	v_pk_fma_f32 v[242:243], v[146:147], v[234:235], v[242:243] op_sel_hi:[0,1,1] neg_lo:[1,0,0] neg_hi:[1,0,0]
	v_pk_fma_f32 v[244:245], v[146:147], v[236:237], v[244:245] op_sel_hi:[0,1,1] neg_lo:[1,0,0] neg_hi:[1,0,0]
	v_pk_fma_f32 v[138:139], v[138:139], v[238:239], v[242:243]
	v_pk_fma_f32 v[140:141], v[140:141], v[240:241], v[244:245]
	s_waitcnt lgkmcnt(6)
	v_pk_mul_f32 v[144:145], v[138:139], v[164:165]
	v_pk_fma_f32 v[144:145], v[140:141], v[166:167], v[144:145]
	v_add_f32 v146, v144, v145
	ds_read_b128 v[208:211], v10 offset:27648
	ds_read_b128 v[212:215], v10 offset:27904
	ds_read_b128 v[216:219], v10 offset:28160
	ds_read_b128 v[220:223], v10 offset:28416
	ds_read_b128 v[224:227], v10 offset:28672
	ds_read_b32 v228, v11 offset:27648
	v_add_f32_dpp v146, v146, v146 quad_perm:[1,0,3,2] row_mask:0xf bank_mask:0xf bound_ctrl:1
	v_pk_mul_f32 v[246:247], v[138:139], v[246:247]
	v_pk_fma_f32 v[246:247], v[140:141], v[248:249], v[246:247]
	v_add_f32_dpp v146, v146, v146 quad_perm:[2,3,0,1] row_mask:0xf bank_mask:0xf bound_ctrl:1
	v_add_f32 v163, v246, v247
	v_pk_mul_f32 v[176:177], v[176:177], v[184:185] op_sel_hi:[1,0]
	v_add_f32_dpp v146, v146, v146 row_half_mirror row_mask:0xf bank_mask:0xf bound_ctrl:1
	v_pk_mul_f32 v[178:179], v[178:179], v[184:185] op_sel_hi:[1,0]
	s_nop 0
	v_add_f32_dpp v146, v146, v146 row_mirror row_mask:0xf bank_mask:0xf bound_ctrl:1
	v_pk_fma_f32 v[176:177], v[146:147], v[168:169], v[176:177] op_sel_hi:[0,1,1] neg_lo:[1,0,0] neg_hi:[1,0,0]
	v_pk_fma_f32 v[178:179], v[146:147], v[170:171], v[178:179] op_sel_hi:[0,1,1] neg_lo:[1,0,0] neg_hi:[1,0,0]
	v_pk_fma_f32 v[138:139], v[138:139], v[172:173], v[176:177]
	v_pk_fma_f32 v[140:141], v[140:141], v[174:175], v[178:179]
	s_waitcnt lgkmcnt(6)
	v_pk_mul_f32 v[144:145], v[138:139], v[186:187]
	v_pk_fma_f32 v[144:145], v[140:141], v[188:189], v[144:145]
	v_add_f32 v146, v144, v145
	v_add_f32_dpp v230, v148, v148 row_mirror row_mask:0xf bank_mask:0x3 bound_ctrl:1
	v_add_f32_dpp v230, v156, v156 row_mirror row_mask:0xf bank_mask:0xc bound_ctrl:1
	v_add_f32_dpp v231, v149, v149 row_mirror row_mask:0xf bank_mask:0x3 bound_ctrl:1
	v_add_f32_dpp v231, v157, v157 row_mirror row_mask:0xf bank_mask:0xc bound_ctrl:1
	v_add_f32_dpp v232, v150, v150 row_mirror row_mask:0xf bank_mask:0x3 bound_ctrl:1
	v_add_f32_dpp v232, v158, v158 row_mirror row_mask:0xf bank_mask:0xc bound_ctrl:1
	v_add_f32_dpp v233, v151, v151 row_mirror row_mask:0xf bank_mask:0x3 bound_ctrl:1
	v_add_f32_dpp v233, v159, v159 row_mirror row_mask:0xf bank_mask:0xc bound_ctrl:1
	v_add_f32_dpp v234, v152, v152 row_mirror row_mask:0xf bank_mask:0x3 bound_ctrl:1
	v_add_f32_dpp v234, v160, v160 row_mirror row_mask:0xf bank_mask:0xc bound_ctrl:1
	v_add_f32_dpp v235, v153, v153 row_mirror row_mask:0xf bank_mask:0x3 bound_ctrl:1
	v_add_f32_dpp v235, v161, v161 row_mirror row_mask:0xf bank_mask:0xc bound_ctrl:1
	v_add_f32_dpp v236, v154, v154 row_mirror row_mask:0xf bank_mask:0x3 bound_ctrl:1
	v_add_f32_dpp v236, v162, v162 row_mirror row_mask:0xf bank_mask:0xc bound_ctrl:1
	v_add_f32_dpp v237, v155, v155 row_mirror row_mask:0xf bank_mask:0x3 bound_ctrl:1
	v_add_f32_dpp v237, v163, v163 row_mirror row_mask:0xf bank_mask:0xc bound_ctrl:1
	v_add_f32_dpp v238, v230, v230 row_half_mirror row_mask:0xf bank_mask:0x5 bound_ctrl:1
	v_add_f32_dpp v238, v234, v234 row_half_mirror row_mask:0xf bank_mask:0xa bound_ctrl:1
	v_add_f32_dpp v239, v231, v231 row_half_mirror row_mask:0xf bank_mask:0x5 bound_ctrl:1
	v_add_f32_dpp v239, v235, v235 row_half_mirror row_mask:0xf bank_mask:0xa bound_ctrl:1
	v_add_f32_dpp v240, v232, v232 row_half_mirror row_mask:0xf bank_mask:0x5 bound_ctrl:1
	v_add_f32_dpp v240, v236, v236 row_half_mirror row_mask:0xf bank_mask:0xa bound_ctrl:1
	v_add_f32_dpp v241, v233, v233 row_half_mirror row_mask:0xf bank_mask:0x5 bound_ctrl:1
	v_add_f32_dpp v241, v237, v237 row_half_mirror row_mask:0xf bank_mask:0xa bound_ctrl:1
	s_mov_b32 vcc_lo, 0xcccccccc
	s_mov_b32 vcc_hi, 0xcccccccc
	v_cndmask_b32 v244, v240, v238, vcc
	v_cndmask_b32 v245, v241, v239, vcc
	v_cndmask_b32 v242, v238, v240, vcc
	v_cndmask_b32 v243, v239, v241, vcc
	v_add_f32_dpp v242, v244, v242 quad_perm:[2,3,0,1] row_mask:0xf bank_mask:0xf bound_ctrl:1
	v_add_f32_dpp v243, v245, v243 quad_perm:[2,3,0,1] row_mask:0xf bank_mask:0xf bound_ctrl:1
	s_mov_b32 vcc_lo, 0xaaaaaaaa
	s_mov_b32 vcc_hi, 0xaaaaaaaa
	v_cndmask_b32 v244, v243, v242, vcc
	v_cndmask_b32 v245, v242, v243, vcc
	s_nop 0
	v_add_f32_dpp v18, v244, v245 quad_perm:[1,0,3,2] row_mask:0xf bank_mask:0xf bound_ctrl:1
	ds_read_b128 v[230:233], v10 offset:29184
	ds_read_b128 v[234:237], v10 offset:29440
	ds_read_b128 v[238:241], v10 offset:29696
	ds_read_b128 v[242:245], v10 offset:29952
	ds_read_b128 v[246:249], v10 offset:30208
	ds_read_b32 v250, v11 offset:29184
	v_add_f32_dpp v146, v146, v146 quad_perm:[1,0,3,2] row_mask:0xf bank_mask:0xf bound_ctrl:1
	v_pk_mul_f32 v[180:181], v[138:139], v[180:181]
	v_pk_fma_f32 v[180:181], v[140:141], v[182:183], v[180:181]
	v_add_f32_dpp v146, v146, v146 quad_perm:[2,3,0,1] row_mask:0xf bank_mask:0xf bound_ctrl:1
	v_add_f32 v148, v180, v181
	v_pk_mul_f32 v[198:199], v[198:199], v[206:207] op_sel_hi:[1,0]
	v_add_f32_dpp v146, v146, v146 row_half_mirror row_mask:0xf bank_mask:0xf bound_ctrl:1
	v_pk_mul_f32 v[200:201], v[200:201], v[206:207] op_sel_hi:[1,0]
	s_nop 0
	v_add_f32_dpp v146, v146, v146 row_mirror row_mask:0xf bank_mask:0xf bound_ctrl:1
	v_pk_fma_f32 v[198:199], v[146:147], v[190:191], v[198:199] op_sel_hi:[0,1,1] neg_lo:[1,0,0] neg_hi:[1,0,0]
	v_pk_fma_f32 v[200:201], v[146:147], v[192:193], v[200:201] op_sel_hi:[0,1,1] neg_lo:[1,0,0] neg_hi:[1,0,0]
	v_pk_fma_f32 v[138:139], v[138:139], v[194:195], v[198:199]
	v_pk_fma_f32 v[140:141], v[140:141], v[196:197], v[200:201]
	s_waitcnt lgkmcnt(6)
	v_pk_mul_f32 v[144:145], v[138:139], v[208:209]
	v_pk_fma_f32 v[144:145], v[140:141], v[210:211], v[144:145]
	v_add_f32 v146, v144, v145
	ds_read_b128 v[164:167], v10 offset:30720
	ds_read_b128 v[168:171], v10 offset:30976
	ds_read_b128 v[172:175], v10 offset:31232
	ds_read_b128 v[176:179], v10 offset:31488
	ds_read_b128 v[180:183], v10 offset:31744
	ds_read_b32 v184, v11 offset:30720
	v_add_f32_dpp v146, v146, v146 quad_perm:[1,0,3,2] row_mask:0xf bank_mask:0xf bound_ctrl:1
	v_pk_mul_f32 v[202:203], v[138:139], v[202:203]
	v_pk_fma_f32 v[202:203], v[140:141], v[204:205], v[202:203]
	v_add_f32_dpp v146, v146, v146 quad_perm:[2,3,0,1] row_mask:0xf bank_mask:0xf bound_ctrl:1
	v_add_f32 v149, v202, v203
	v_pk_mul_f32 v[220:221], v[220:221], v[228:229] op_sel_hi:[1,0]
	v_add_f32_dpp v146, v146, v146 row_half_mirror row_mask:0xf bank_mask:0xf bound_ctrl:1
	v_pk_mul_f32 v[222:223], v[222:223], v[228:229] op_sel_hi:[1,0]
	s_nop 0
	v_add_f32_dpp v146, v146, v146 row_mirror row_mask:0xf bank_mask:0xf bound_ctrl:1
	v_pk_fma_f32 v[220:221], v[146:147], v[212:213], v[220:221] op_sel_hi:[0,1,1] neg_lo:[1,0,0] neg_hi:[1,0,0]
	v_pk_fma_f32 v[222:223], v[146:147], v[214:215], v[222:223] op_sel_hi:[0,1,1] neg_lo:[1,0,0] neg_hi:[1,0,0]
	v_pk_fma_f32 v[138:139], v[138:139], v[216:217], v[220:221]
	v_pk_fma_f32 v[140:141], v[140:141], v[218:219], v[222:223]
	s_waitcnt lgkmcnt(6)
	v_pk_mul_f32 v[144:145], v[138:139], v[230:231]
	v_pk_fma_f32 v[144:145], v[140:141], v[232:233], v[144:145]
	v_add_f32 v146, v144, v145
	ds_read_b128 v[186:189], v10 offset:32256
	ds_read_b128 v[190:193], v10 offset:32512
	ds_read_b128 v[194:197], v10 offset:32768
	ds_read_b128 v[198:201], v10 offset:33024
	ds_read_b128 v[202:205], v10 offset:33280
	ds_read_b32 v206, v11 offset:32256
	v_add_f32_dpp v146, v146, v146 quad_perm:[1,0,3,2] row_mask:0xf bank_mask:0xf bound_ctrl:1
	v_pk_mul_f32 v[224:225], v[138:139], v[224:225]
	v_pk_fma_f32 v[224:225], v[140:141], v[226:227], v[224:225]
	v_add_f32_dpp v146, v146, v146 quad_perm:[2,3,0,1] row_mask:0xf bank_mask:0xf bound_ctrl:1
	v_add_f32 v150, v224, v225
	v_pk_mul_f32 v[242:243], v[242:243], v[250:251] op_sel_hi:[1,0]
	v_add_f32_dpp v146, v146, v146 row_half_mirror row_mask:0xf bank_mask:0xf bound_ctrl:1
	v_pk_mul_f32 v[244:245], v[244:245], v[250:251] op_sel_hi:[1,0]
	s_nop 0
	v_add_f32_dpp v146, v146, v146 row_mirror row_mask:0xf bank_mask:0xf bound_ctrl:1
	v_pk_fma_f32 v[242:243], v[146:147], v[234:235], v[242:243] op_sel_hi:[0,1,1] neg_lo:[1,0,0] neg_hi:[1,0,0]
	v_pk_fma_f32 v[244:245], v[146:147], v[236:237], v[244:245] op_sel_hi:[0,1,1] neg_lo:[1,0,0] neg_hi:[1,0,0]
	v_pk_fma_f32 v[138:139], v[138:139], v[238:239], v[242:243]
	v_pk_fma_f32 v[140:141], v[140:141], v[240:241], v[244:245]
	s_waitcnt lgkmcnt(6)
	v_pk_mul_f32 v[144:145], v[138:139], v[164:165]
	v_pk_fma_f32 v[144:145], v[140:141], v[166:167], v[144:145]
	v_add_f32 v146, v144, v145
	ds_read_b128 v[208:211], v10 offset:33792
	ds_read_b128 v[212:215], v10 offset:34048
	ds_read_b128 v[216:219], v10 offset:34304
	ds_read_b128 v[220:223], v10 offset:34560
	ds_read_b128 v[224:227], v10 offset:34816
	ds_read_b32 v228, v11 offset:33792
	v_add_f32_dpp v146, v146, v146 quad_perm:[1,0,3,2] row_mask:0xf bank_mask:0xf bound_ctrl:1
	v_pk_mul_f32 v[246:247], v[138:139], v[246:247]
	v_pk_fma_f32 v[246:247], v[140:141], v[248:249], v[246:247]
	v_add_f32_dpp v146, v146, v146 quad_perm:[2,3,0,1] row_mask:0xf bank_mask:0xf bound_ctrl:1
	v_add_f32 v151, v246, v247
	v_pk_mul_f32 v[176:177], v[176:177], v[184:185] op_sel_hi:[1,0]
	v_add_f32_dpp v146, v146, v146 row_half_mirror row_mask:0xf bank_mask:0xf bound_ctrl:1
	v_pk_mul_f32 v[178:179], v[178:179], v[184:185] op_sel_hi:[1,0]
	s_nop 0
	v_add_f32_dpp v146, v146, v146 row_mirror row_mask:0xf bank_mask:0xf bound_ctrl:1
	v_pk_fma_f32 v[176:177], v[146:147], v[168:169], v[176:177] op_sel_hi:[0,1,1] neg_lo:[1,0,0] neg_hi:[1,0,0]
	v_pk_fma_f32 v[178:179], v[146:147], v[170:171], v[178:179] op_sel_hi:[0,1,1] neg_lo:[1,0,0] neg_hi:[1,0,0]
	v_pk_fma_f32 v[138:139], v[138:139], v[172:173], v[176:177]
	v_pk_fma_f32 v[140:141], v[140:141], v[174:175], v[178:179]
	s_waitcnt lgkmcnt(6)
	v_pk_mul_f32 v[144:145], v[138:139], v[186:187]
	v_pk_fma_f32 v[144:145], v[140:141], v[188:189], v[144:145]
	v_add_f32 v146, v144, v145
	ds_read_b128 v[230:233], v10 offset:35328
	ds_read_b128 v[234:237], v10 offset:35584
	ds_read_b128 v[238:241], v10 offset:35840
	ds_read_b128 v[242:245], v10 offset:36096
	ds_read_b128 v[246:249], v10 offset:36352
	ds_read_b32 v250, v11 offset:35328
	v_add_f32_dpp v146, v146, v146 quad_perm:[1,0,3,2] row_mask:0xf bank_mask:0xf bound_ctrl:1
	v_pk_mul_f32 v[180:181], v[138:139], v[180:181]
	v_pk_fma_f32 v[180:181], v[140:141], v[182:183], v[180:181]
	v_add_f32_dpp v146, v146, v146 quad_perm:[2,3,0,1] row_mask:0xf bank_mask:0xf bound_ctrl:1
	v_add_f32 v152, v180, v181
	v_pk_mul_f32 v[198:199], v[198:199], v[206:207] op_sel_hi:[1,0]
	v_add_f32_dpp v146, v146, v146 row_half_mirror row_mask:0xf bank_mask:0xf bound_ctrl:1
	v_pk_mul_f32 v[200:201], v[200:201], v[206:207] op_sel_hi:[1,0]
	s_nop 0
	v_add_f32_dpp v146, v146, v146 row_mirror row_mask:0xf bank_mask:0xf bound_ctrl:1
	v_pk_fma_f32 v[198:199], v[146:147], v[190:191], v[198:199] op_sel_hi:[0,1,1] neg_lo:[1,0,0] neg_hi:[1,0,0]
	v_pk_fma_f32 v[200:201], v[146:147], v[192:193], v[200:201] op_sel_hi:[0,1,1] neg_lo:[1,0,0] neg_hi:[1,0,0]
	v_pk_fma_f32 v[138:139], v[138:139], v[194:195], v[198:199]
	v_pk_fma_f32 v[140:141], v[140:141], v[196:197], v[200:201]
	s_waitcnt lgkmcnt(6)
	v_pk_mul_f32 v[144:145], v[138:139], v[208:209]
	v_pk_fma_f32 v[144:145], v[140:141], v[210:211], v[144:145]
	v_add_f32 v146, v144, v145
	ds_read_b128 v[164:167], v10 offset:36864
	ds_read_b128 v[168:171], v10 offset:37120
	ds_read_b128 v[172:175], v10 offset:37376
	ds_read_b128 v[176:179], v10 offset:37632
	ds_read_b128 v[180:183], v10 offset:37888
	ds_read_b32 v184, v11 offset:36864
	v_add_f32_dpp v146, v146, v146 quad_perm:[1,0,3,2] row_mask:0xf bank_mask:0xf bound_ctrl:1
	v_pk_mul_f32 v[202:203], v[138:139], v[202:203]
	v_pk_fma_f32 v[202:203], v[140:141], v[204:205], v[202:203]
	v_add_f32_dpp v146, v146, v146 quad_perm:[2,3,0,1] row_mask:0xf bank_mask:0xf bound_ctrl:1
	v_add_f32 v153, v202, v203
	v_pk_mul_f32 v[220:221], v[220:221], v[228:229] op_sel_hi:[1,0]
	v_add_f32_dpp v146, v146, v146 row_half_mirror row_mask:0xf bank_mask:0xf bound_ctrl:1
	v_pk_mul_f32 v[222:223], v[222:223], v[228:229] op_sel_hi:[1,0]
	s_nop 0
	v_add_f32_dpp v146, v146, v146 row_mirror row_mask:0xf bank_mask:0xf bound_ctrl:1
	v_pk_fma_f32 v[220:221], v[146:147], v[212:213], v[220:221] op_sel_hi:[0,1,1] neg_lo:[1,0,0] neg_hi:[1,0,0]
	v_pk_fma_f32 v[222:223], v[146:147], v[214:215], v[222:223] op_sel_hi:[0,1,1] neg_lo:[1,0,0] neg_hi:[1,0,0]
	v_pk_fma_f32 v[138:139], v[138:139], v[216:217], v[220:221]
	v_pk_fma_f32 v[140:141], v[140:141], v[218:219], v[222:223]
	s_waitcnt lgkmcnt(6)
	v_pk_mul_f32 v[144:145], v[138:139], v[230:231]
	v_pk_fma_f32 v[144:145], v[140:141], v[232:233], v[144:145]
	v_add_f32 v146, v144, v145
	ds_read_b128 v[186:189], v10 offset:38400
	ds_read_b128 v[190:193], v10 offset:38656
	ds_read_b128 v[194:197], v10 offset:38912
	ds_read_b128 v[198:201], v10 offset:39168
	ds_read_b128 v[202:205], v10 offset:39424
	ds_read_b32 v206, v11 offset:38400
	v_add_f32_dpp v146, v146, v146 quad_perm:[1,0,3,2] row_mask:0xf bank_mask:0xf bound_ctrl:1
	v_pk_mul_f32 v[224:225], v[138:139], v[224:225]
	v_pk_fma_f32 v[224:225], v[140:141], v[226:227], v[224:225]
	v_add_f32_dpp v146, v146, v146 quad_perm:[2,3,0,1] row_mask:0xf bank_mask:0xf bound_ctrl:1
	v_add_f32 v154, v224, v225
	v_pk_mul_f32 v[242:243], v[242:243], v[250:251] op_sel_hi:[1,0]
	v_add_f32_dpp v146, v146, v146 row_half_mirror row_mask:0xf bank_mask:0xf bound_ctrl:1
	v_pk_mul_f32 v[244:245], v[244:245], v[250:251] op_sel_hi:[1,0]
	s_nop 0
	v_add_f32_dpp v146, v146, v146 row_mirror row_mask:0xf bank_mask:0xf bound_ctrl:1
	v_pk_fma_f32 v[242:243], v[146:147], v[234:235], v[242:243] op_sel_hi:[0,1,1] neg_lo:[1,0,0] neg_hi:[1,0,0]
	v_pk_fma_f32 v[244:245], v[146:147], v[236:237], v[244:245] op_sel_hi:[0,1,1] neg_lo:[1,0,0] neg_hi:[1,0,0]
	v_pk_fma_f32 v[138:139], v[138:139], v[238:239], v[242:243]
	v_pk_fma_f32 v[140:141], v[140:141], v[240:241], v[244:245]
	s_waitcnt lgkmcnt(6)
	v_pk_mul_f32 v[144:145], v[138:139], v[164:165]
	v_pk_fma_f32 v[144:145], v[140:141], v[166:167], v[144:145]
	v_add_f32 v146, v144, v145
	ds_read_b128 v[208:211], v10 offset:39936
	ds_read_b128 v[212:215], v10 offset:40192
	ds_read_b128 v[216:219], v10 offset:40448
	ds_read_b128 v[220:223], v10 offset:40704
	ds_read_b128 v[224:227], v10 offset:40960
	ds_read_b32 v228, v11 offset:39936
	v_add_f32_dpp v146, v146, v146 quad_perm:[1,0,3,2] row_mask:0xf bank_mask:0xf bound_ctrl:1
	v_pk_mul_f32 v[246:247], v[138:139], v[246:247]
	v_pk_fma_f32 v[246:247], v[140:141], v[248:249], v[246:247]
	v_add_f32_dpp v146, v146, v146 quad_perm:[2,3,0,1] row_mask:0xf bank_mask:0xf bound_ctrl:1
	v_add_f32 v155, v246, v247
	v_pk_mul_f32 v[176:177], v[176:177], v[184:185] op_sel_hi:[1,0]
	v_add_f32_dpp v146, v146, v146 row_half_mirror row_mask:0xf bank_mask:0xf bound_ctrl:1
	v_pk_mul_f32 v[178:179], v[178:179], v[184:185] op_sel_hi:[1,0]
	s_nop 0
	v_add_f32_dpp v146, v146, v146 row_mirror row_mask:0xf bank_mask:0xf bound_ctrl:1
	v_pk_fma_f32 v[176:177], v[146:147], v[168:169], v[176:177] op_sel_hi:[0,1,1] neg_lo:[1,0,0] neg_hi:[1,0,0]
	v_pk_fma_f32 v[178:179], v[146:147], v[170:171], v[178:179] op_sel_hi:[0,1,1] neg_lo:[1,0,0] neg_hi:[1,0,0]
	v_pk_fma_f32 v[138:139], v[138:139], v[172:173], v[176:177]
	v_pk_fma_f32 v[140:141], v[140:141], v[174:175], v[178:179]
	s_waitcnt lgkmcnt(6)
	v_pk_mul_f32 v[144:145], v[138:139], v[186:187]
	v_pk_fma_f32 v[144:145], v[140:141], v[188:189], v[144:145]
	v_add_f32 v146, v144, v145
	ds_read_b128 v[230:233], v10 offset:41472
	ds_read_b128 v[234:237], v10 offset:41728
	ds_read_b128 v[238:241], v10 offset:41984
	ds_read_b128 v[242:245], v10 offset:42240
	ds_read_b128 v[246:249], v10 offset:42496
	ds_read_b32 v250, v11 offset:41472
	v_add_f32_dpp v146, v146, v146 quad_perm:[1,0,3,2] row_mask:0xf bank_mask:0xf bound_ctrl:1
	v_pk_mul_f32 v[180:181], v[138:139], v[180:181]
	v_pk_fma_f32 v[180:181], v[140:141], v[182:183], v[180:181]
	v_add_f32_dpp v146, v146, v146 quad_perm:[2,3,0,1] row_mask:0xf bank_mask:0xf bound_ctrl:1
	v_add_f32 v156, v180, v181
	v_pk_mul_f32 v[198:199], v[198:199], v[206:207] op_sel_hi:[1,0]
	v_add_f32_dpp v146, v146, v146 row_half_mirror row_mask:0xf bank_mask:0xf bound_ctrl:1
	v_pk_mul_f32 v[200:201], v[200:201], v[206:207] op_sel_hi:[1,0]
	s_nop 0
	v_add_f32_dpp v146, v146, v146 row_mirror row_mask:0xf bank_mask:0xf bound_ctrl:1
	v_pk_fma_f32 v[198:199], v[146:147], v[190:191], v[198:199] op_sel_hi:[0,1,1] neg_lo:[1,0,0] neg_hi:[1,0,0]
	v_pk_fma_f32 v[200:201], v[146:147], v[192:193], v[200:201] op_sel_hi:[0,1,1] neg_lo:[1,0,0] neg_hi:[1,0,0]
	v_pk_fma_f32 v[138:139], v[138:139], v[194:195], v[198:199]
	v_pk_fma_f32 v[140:141], v[140:141], v[196:197], v[200:201]
	s_waitcnt lgkmcnt(6)
	v_pk_mul_f32 v[144:145], v[138:139], v[208:209]
	v_pk_fma_f32 v[144:145], v[140:141], v[210:211], v[144:145]
	v_add_f32 v146, v144, v145
	ds_read_b128 v[164:167], v10 offset:43008
	ds_read_b128 v[168:171], v10 offset:43264
	ds_read_b128 v[172:175], v10 offset:43520
	ds_read_b128 v[176:179], v10 offset:43776
	ds_read_b128 v[180:183], v10 offset:44032
	ds_read_b32 v184, v11 offset:43008
	v_add_f32_dpp v146, v146, v146 quad_perm:[1,0,3,2] row_mask:0xf bank_mask:0xf bound_ctrl:1
	v_pk_mul_f32 v[202:203], v[138:139], v[202:203]
	v_pk_fma_f32 v[202:203], v[140:141], v[204:205], v[202:203]
	v_add_f32_dpp v146, v146, v146 quad_perm:[2,3,0,1] row_mask:0xf bank_mask:0xf bound_ctrl:1
	v_add_f32 v157, v202, v203
	v_pk_mul_f32 v[220:221], v[220:221], v[228:229] op_sel_hi:[1,0]
	v_add_f32_dpp v146, v146, v146 row_half_mirror row_mask:0xf bank_mask:0xf bound_ctrl:1
	v_pk_mul_f32 v[222:223], v[222:223], v[228:229] op_sel_hi:[1,0]
	s_nop 0
	v_add_f32_dpp v146, v146, v146 row_mirror row_mask:0xf bank_mask:0xf bound_ctrl:1
	v_pk_fma_f32 v[220:221], v[146:147], v[212:213], v[220:221] op_sel_hi:[0,1,1] neg_lo:[1,0,0] neg_hi:[1,0,0]
	v_pk_fma_f32 v[222:223], v[146:147], v[214:215], v[222:223] op_sel_hi:[0,1,1] neg_lo:[1,0,0] neg_hi:[1,0,0]
	v_pk_fma_f32 v[138:139], v[138:139], v[216:217], v[220:221]
	v_pk_fma_f32 v[140:141], v[140:141], v[218:219], v[222:223]
	s_waitcnt lgkmcnt(6)
	v_pk_mul_f32 v[144:145], v[138:139], v[230:231]
	v_pk_fma_f32 v[144:145], v[140:141], v[232:233], v[144:145]
	v_add_f32 v146, v144, v145
	ds_read_b128 v[186:189], v10 offset:44544
	ds_read_b128 v[190:193], v10 offset:44800
	ds_read_b128 v[194:197], v10 offset:45056
	ds_read_b128 v[198:201], v10 offset:45312
	ds_read_b128 v[202:205], v10 offset:45568
	ds_read_b32 v206, v11 offset:44544
	v_add_f32_dpp v146, v146, v146 quad_perm:[1,0,3,2] row_mask:0xf bank_mask:0xf bound_ctrl:1
	v_pk_mul_f32 v[224:225], v[138:139], v[224:225]
	v_pk_fma_f32 v[224:225], v[140:141], v[226:227], v[224:225]
	v_add_f32_dpp v146, v146, v146 quad_perm:[2,3,0,1] row_mask:0xf bank_mask:0xf bound_ctrl:1
	v_add_f32 v158, v224, v225
	v_pk_mul_f32 v[242:243], v[242:243], v[250:251] op_sel_hi:[1,0]
	v_add_f32_dpp v146, v146, v146 row_half_mirror row_mask:0xf bank_mask:0xf bound_ctrl:1
	v_pk_mul_f32 v[244:245], v[244:245], v[250:251] op_sel_hi:[1,0]
	s_nop 0
	v_add_f32_dpp v146, v146, v146 row_mirror row_mask:0xf bank_mask:0xf bound_ctrl:1
	v_pk_fma_f32 v[242:243], v[146:147], v[234:235], v[242:243] op_sel_hi:[0,1,1] neg_lo:[1,0,0] neg_hi:[1,0,0]
	v_pk_fma_f32 v[244:245], v[146:147], v[236:237], v[244:245] op_sel_hi:[0,1,1] neg_lo:[1,0,0] neg_hi:[1,0,0]
	v_pk_fma_f32 v[138:139], v[138:139], v[238:239], v[242:243]
	v_pk_fma_f32 v[140:141], v[140:141], v[240:241], v[244:245]
	s_waitcnt lgkmcnt(6)
	v_pk_mul_f32 v[144:145], v[138:139], v[164:165]
	v_pk_fma_f32 v[144:145], v[140:141], v[166:167], v[144:145]
	v_add_f32 v146, v144, v145
	ds_read_b128 v[208:211], v10 offset:46080
	ds_read_b128 v[212:215], v10 offset:46336
	ds_read_b128 v[216:219], v10 offset:46592
	ds_read_b128 v[220:223], v10 offset:46848
	ds_read_b128 v[224:227], v10 offset:47104
	ds_read_b32 v228, v11 offset:46080
	v_add_f32_dpp v146, v146, v146 quad_perm:[1,0,3,2] row_mask:0xf bank_mask:0xf bound_ctrl:1
	v_pk_mul_f32 v[246:247], v[138:139], v[246:247]
	v_pk_fma_f32 v[246:247], v[140:141], v[248:249], v[246:247]
	v_add_f32_dpp v146, v146, v146 quad_perm:[2,3,0,1] row_mask:0xf bank_mask:0xf bound_ctrl:1
	v_add_f32 v159, v246, v247
	v_pk_mul_f32 v[176:177], v[176:177], v[184:185] op_sel_hi:[1,0]
	v_add_f32_dpp v146, v146, v146 row_half_mirror row_mask:0xf bank_mask:0xf bound_ctrl:1
	v_pk_mul_f32 v[178:179], v[178:179], v[184:185] op_sel_hi:[1,0]
	s_nop 0
	v_add_f32_dpp v146, v146, v146 row_mirror row_mask:0xf bank_mask:0xf bound_ctrl:1
	v_pk_fma_f32 v[176:177], v[146:147], v[168:169], v[176:177] op_sel_hi:[0,1,1] neg_lo:[1,0,0] neg_hi:[1,0,0]
	v_pk_fma_f32 v[178:179], v[146:147], v[170:171], v[178:179] op_sel_hi:[0,1,1] neg_lo:[1,0,0] neg_hi:[1,0,0]
	v_pk_fma_f32 v[138:139], v[138:139], v[172:173], v[176:177]
	v_pk_fma_f32 v[140:141], v[140:141], v[174:175], v[178:179]
	s_waitcnt lgkmcnt(6)
	v_pk_mul_f32 v[144:145], v[138:139], v[186:187]
	v_pk_fma_f32 v[144:145], v[140:141], v[188:189], v[144:145]
	v_add_f32 v146, v144, v145
	ds_read_b128 v[230:233], v10 offset:47616
	ds_read_b128 v[234:237], v10 offset:47872
	ds_read_b128 v[238:241], v10 offset:48128
	ds_read_b128 v[242:245], v10 offset:48384
	ds_read_b128 v[246:249], v10 offset:48640
	ds_read_b32 v250, v11 offset:47616
	v_add_f32_dpp v146, v146, v146 quad_perm:[1,0,3,2] row_mask:0xf bank_mask:0xf bound_ctrl:1
	v_pk_mul_f32 v[180:181], v[138:139], v[180:181]
	v_pk_fma_f32 v[180:181], v[140:141], v[182:183], v[180:181]
	v_add_f32_dpp v146, v146, v146 quad_perm:[2,3,0,1] row_mask:0xf bank_mask:0xf bound_ctrl:1
	v_add_f32 v160, v180, v181
	v_pk_mul_f32 v[198:199], v[198:199], v[206:207] op_sel_hi:[1,0]
	v_add_f32_dpp v146, v146, v146 row_half_mirror row_mask:0xf bank_mask:0xf bound_ctrl:1
	v_pk_mul_f32 v[200:201], v[200:201], v[206:207] op_sel_hi:[1,0]
	s_nop 0
	v_add_f32_dpp v146, v146, v146 row_mirror row_mask:0xf bank_mask:0xf bound_ctrl:1
	v_pk_fma_f32 v[198:199], v[146:147], v[190:191], v[198:199] op_sel_hi:[0,1,1] neg_lo:[1,0,0] neg_hi:[1,0,0]
	v_pk_fma_f32 v[200:201], v[146:147], v[192:193], v[200:201] op_sel_hi:[0,1,1] neg_lo:[1,0,0] neg_hi:[1,0,0]
	v_pk_fma_f32 v[138:139], v[138:139], v[194:195], v[198:199]
	v_pk_fma_f32 v[140:141], v[140:141], v[196:197], v[200:201]
	s_waitcnt lgkmcnt(6)
	v_pk_mul_f32 v[144:145], v[138:139], v[208:209]
	v_pk_fma_f32 v[144:145], v[140:141], v[210:211], v[144:145]
	v_add_f32 v146, v144, v145
	s_nop 1
	v_add_f32_dpp v146, v146, v146 quad_perm:[1,0,3,2] row_mask:0xf bank_mask:0xf bound_ctrl:1
	v_pk_mul_f32 v[202:203], v[138:139], v[202:203]
	v_pk_fma_f32 v[202:203], v[140:141], v[204:205], v[202:203]
	v_add_f32_dpp v146, v146, v146 quad_perm:[2,3,0,1] row_mask:0xf bank_mask:0xf bound_ctrl:1
	v_add_f32 v161, v202, v203
	v_pk_mul_f32 v[220:221], v[220:221], v[228:229] op_sel_hi:[1,0]
	v_add_f32_dpp v146, v146, v146 row_half_mirror row_mask:0xf bank_mask:0xf bound_ctrl:1
	v_pk_mul_f32 v[222:223], v[222:223], v[228:229] op_sel_hi:[1,0]
	s_nop 0
	v_add_f32_dpp v146, v146, v146 row_mirror row_mask:0xf bank_mask:0xf bound_ctrl:1
	v_pk_fma_f32 v[220:221], v[146:147], v[212:213], v[220:221] op_sel_hi:[0,1,1] neg_lo:[1,0,0] neg_hi:[1,0,0]
	v_pk_fma_f32 v[222:223], v[146:147], v[214:215], v[222:223] op_sel_hi:[0,1,1] neg_lo:[1,0,0] neg_hi:[1,0,0]
	v_pk_fma_f32 v[138:139], v[138:139], v[216:217], v[220:221]
	v_pk_fma_f32 v[140:141], v[140:141], v[218:219], v[222:223]
	s_waitcnt lgkmcnt(0)
	v_pk_mul_f32 v[144:145], v[138:139], v[230:231]
	v_pk_fma_f32 v[144:145], v[140:141], v[232:233], v[144:145]
	v_add_f32 v146, v144, v145
	s_nop 1
	v_add_f32_dpp v146, v146, v146 quad_perm:[1,0,3,2] row_mask:0xf bank_mask:0xf bound_ctrl:1
	v_pk_mul_f32 v[224:225], v[138:139], v[224:225]
	v_pk_fma_f32 v[224:225], v[140:141], v[226:227], v[224:225]
	v_add_f32_dpp v146, v146, v146 quad_perm:[2,3,0,1] row_mask:0xf bank_mask:0xf bound_ctrl:1
	v_add_f32 v162, v224, v225
	v_pk_mul_f32 v[242:243], v[242:243], v[250:251] op_sel_hi:[1,0]
	v_add_f32_dpp v146, v146, v146 row_half_mirror row_mask:0xf bank_mask:0xf bound_ctrl:1
	v_pk_mul_f32 v[244:245], v[244:245], v[250:251] op_sel_hi:[1,0]
	s_nop 0
	v_add_f32_dpp v146, v146, v146 row_mirror row_mask:0xf bank_mask:0xf bound_ctrl:1
	v_pk_fma_f32 v[242:243], v[146:147], v[234:235], v[242:243] op_sel_hi:[0,1,1] neg_lo:[1,0,0] neg_hi:[1,0,0]
	v_pk_fma_f32 v[244:245], v[146:147], v[236:237], v[244:245] op_sel_hi:[0,1,1] neg_lo:[1,0,0] neg_hi:[1,0,0]
	v_pk_fma_f32 v[138:139], v[138:139], v[238:239], v[242:243]
	v_pk_fma_f32 v[140:141], v[140:141], v[240:241], v[244:245]
	v_pk_mul_f32 v[246:247], v[138:139], v[246:247]
	v_pk_fma_f32 v[246:247], v[140:141], v[248:249], v[246:247]
	v_add_f32 v163, v246, v247
	s_nop 0
	v_add_f32_dpp v230, v148, v148 row_mirror row_mask:0xf bank_mask:0x3 bound_ctrl:1
	v_add_f32_dpp v230, v156, v156 row_mirror row_mask:0xf bank_mask:0xc bound_ctrl:1
	v_add_f32_dpp v231, v149, v149 row_mirror row_mask:0xf bank_mask:0x3 bound_ctrl:1
	v_add_f32_dpp v231, v157, v157 row_mirror row_mask:0xf bank_mask:0xc bound_ctrl:1
	v_add_f32_dpp v232, v150, v150 row_mirror row_mask:0xf bank_mask:0x3 bound_ctrl:1
	v_add_f32_dpp v232, v158, v158 row_mirror row_mask:0xf bank_mask:0xc bound_ctrl:1
	v_add_f32_dpp v233, v151, v151 row_mirror row_mask:0xf bank_mask:0x3 bound_ctrl:1
	v_add_f32_dpp v233, v159, v159 row_mirror row_mask:0xf bank_mask:0xc bound_ctrl:1
	v_add_f32_dpp v234, v152, v152 row_mirror row_mask:0xf bank_mask:0x3 bound_ctrl:1
	v_add_f32_dpp v234, v160, v160 row_mirror row_mask:0xf bank_mask:0xc bound_ctrl:1
	v_add_f32_dpp v235, v153, v153 row_mirror row_mask:0xf bank_mask:0x3 bound_ctrl:1
	v_add_f32_dpp v235, v161, v161 row_mirror row_mask:0xf bank_mask:0xc bound_ctrl:1
	v_add_f32_dpp v236, v154, v154 row_mirror row_mask:0xf bank_mask:0x3 bound_ctrl:1
	v_add_f32_dpp v236, v162, v162 row_mirror row_mask:0xf bank_mask:0xc bound_ctrl:1
	v_add_f32_dpp v237, v155, v155 row_mirror row_mask:0xf bank_mask:0x3 bound_ctrl:1
	v_add_f32_dpp v237, v163, v163 row_mirror row_mask:0xf bank_mask:0xc bound_ctrl:1
	v_add_f32_dpp v238, v230, v230 row_half_mirror row_mask:0xf bank_mask:0x5 bound_ctrl:1
	v_add_f32_dpp v238, v234, v234 row_half_mirror row_mask:0xf bank_mask:0xa bound_ctrl:1
	v_add_f32_dpp v239, v231, v231 row_half_mirror row_mask:0xf bank_mask:0x5 bound_ctrl:1
	v_add_f32_dpp v239, v235, v235 row_half_mirror row_mask:0xf bank_mask:0xa bound_ctrl:1
	v_add_f32_dpp v240, v232, v232 row_half_mirror row_mask:0xf bank_mask:0x5 bound_ctrl:1
	v_add_f32_dpp v240, v236, v236 row_half_mirror row_mask:0xf bank_mask:0xa bound_ctrl:1
	v_add_f32_dpp v241, v233, v233 row_half_mirror row_mask:0xf bank_mask:0x5 bound_ctrl:1
	v_add_f32_dpp v241, v237, v237 row_half_mirror row_mask:0xf bank_mask:0xa bound_ctrl:1
	s_mov_b32 vcc_lo, 0xcccccccc
	s_mov_b32 vcc_hi, 0xcccccccc
	v_cndmask_b32 v244, v240, v238, vcc
	v_cndmask_b32 v245, v241, v239, vcc
	v_cndmask_b32 v242, v238, v240, vcc
	v_cndmask_b32 v243, v239, v241, vcc
	v_add_f32_dpp v242, v244, v242 quad_perm:[2,3,0,1] row_mask:0xf bank_mask:0xf bound_ctrl:1
	v_add_f32_dpp v243, v245, v243 quad_perm:[2,3,0,1] row_mask:0xf bank_mask:0xf bound_ctrl:1
	s_mov_b32 vcc_lo, 0xaaaaaaaa
	s_mov_b32 vcc_hi, 0xaaaaaaaa
	v_cndmask_b32 v244, v243, v242, vcc
	v_cndmask_b32 v245, v242, v243, vcc
	s_nop 0
	v_add_f32_dpp v19, v244, v245 quad_perm:[1,0,3,2] row_mask:0xf bank_mask:0xf bound_ctrl:1

; #define SCAN_BAR() asm volatile("s_barrier" ::: "memory")
; __device__ __forceinline__ void scan_unit(const Ctx& C0, const float* scn, int T, int quarter, const float* S0, float* Sout, unsigned char* obase, int mode) {
;     ...
;         for (int k = 0; k < nch; ++k) {
;             const unsigned aq = (unsigned)(size_t)(C.lds + (k & 1) * SLOT_B) + 16u * (unsigned)q, av = (unsigned)(size_t)(C.lds + (k & 1) * SLOT_B) + (320u + (unsigned)irow) * 4u;
;             float osel0, osel1;
;             asm volatile(SCAN_CHUNK_ASM : "+v"(S0x), "+v"(S1x), "+v"(S2x), "+v"(S3x), "=&v"(osel0), "=&v"(osel1) : "v"(aq), "v"(av), "v"(q) : SCAN_CHUNK_CLOBBERS, "memory");
;             if (mode == 0) { *(float*)(obase + (size_t)(k * 32 + q) * UPITCH_B + rl * 4) = osel0; *(float*)(obase + (size_t)(k * 32 + 16 + q) * UPITCH_B + rl * 4) = osel1; }
;             SCAN_BAR();
;         }
;         if (mode == 0) *(f32x4*)(Sout + irow * 64 + 4 * q) = (f32x4){S0x, S1x, S2x, S3x};
	s_addc_u32 s1, s1, 0
	v_add_co_u32_e32 v16, vcc, s8, v14
	s_cmp_lg_u32 s0, 0x5600000
	s_nop 0
	v_addc_co_u32_e32 v17, vcc, 0, v15, vcc
	v_add_co_u32_e32 v14, vcc, 0xfcaa000, v14
	global_store_dword v[16:17], v18, off offset:768
	s_nop 0
	v_addc_co_u32_e32 v15, vcc, 0, v15, vcc
	global_store_dword v[14:15], v19, off offset:768
	s_barrier
	s_cbranch_scc1 .LBB0_685
	v_mov_b32_e32 v2, v138
	v_mov_b32_e32 v13, v139
	v_mov_b32_e32 v12, v140
	v_mov_b32_e32 v8, v141
	v_readlane_b32 s0, v255, 46
	s_add_i32 s0, s3, s0
	s_ashr_i32 s1, s0, 31
	s_lshl_b64 s[0:1], s[0:1], 17
	v_readlane_b32 s3, v253, 26
	s_add_u32 s0, s3, s0
	v_readlane_b32 s3, v253, 27
	s_addc_u32 s1, s3, s1
	s_lshl_b32 s2, s2, 14
	s_add_u32 s0, s0, s2
	s_addc_u32 s1, s1, 0
	v_lshlrev_b32_e32 v0, 8, v0
	v_lshl_add_u64 v[6:7], s[0:1], 0, v[0:1]
	v_mov_b32_e32 v5, v1
	v_lshl_add_u64 v[6:7], v[6:7], 0, v[4:5]
	v_mov_b32_e32 v3, v13
	v_mov_b32_e32 v4, v12
	v_mov_b32_e32 v5, v8
	global_store_dwordx4 v[6:7], v[2:5], off
